# v69 + M0 scratch SGPRs folded into the M0 writes in the K-loops (10 SALU removed)
# baseline (speedup 1.0000x reference)
; #define PG8_STAGE(bufoff, gbase, voff) do { _Pragma("unroll") for (int _i = 0; _i < 2; ++_i) \
;         __builtin_amdgcn_global_load_lds((const unsigned*)((const char*)(gbase) + (voff)[_i]), (PG8_LAS unsigned*)(lds + (bufoff) + ldsw + _i * 8192), 16, 0, 0); } while (0)
; #define PG8_LDA(dst, b, h) do { _Pragma("unroll") for (int m = 0; m < 4; ++m) _Pragma("unroll") for (int k = 0; k < 2; ++k) dst[m][k] = *(const PG8_LAS bf16x8*)(lds + PG8_SA(b, h) + aoff + m * 2048 + k * 1024); } while (0)
; #define PG8_LDB(dst, b, h) do { _Pragma("unroll") for (int n = 0; n < 2; ++n) _Pragma("unroll") for (int k = 0; k < 2; ++k) dst[n][k] = *(const PG8_LAS bf16x8*)(lds + PG8_SB(b, h) + boff + n * 2048 + k * 1024); } while (0)
; #define PG8_MMA(ai, bj, At, Bt) do { __builtin_amdgcn_s_setprio(1); _Pragma("unroll") for (int m = 0; m < 4; ++m) _Pragma("unroll") for (int n = 0; n < 2; ++n) _Pragma("unroll") for (int k = 0; k < 2; ++k) \
;         acc[ai][bj][m][n] = __builtin_amdgcn_mfma_f32_16x16x32_bf16(Bt[n][k], At[m][k], acc[ai][bj][m][n], 0, 0, 0); __builtin_amdgcn_s_setprio(0); } while (0)
; #define PG8_WAIT_V(n) asm volatile("s_waitcnt vmcnt(" #n ")" ::: "memory")
; #define PG8_WAIT_L(n) asm volatile("s_waitcnt lgkmcnt(" #n ")" ::: "memory")
; template <class Epi, class Sched, bool ALIGN_EPI = false, bool SP2 = false>
; __device__ __forceinline__ void gemm_phase(PG8_LAS unsigned char* lds, const Gemm g, const Sched& S, const Epi& E, const int wv) {
;     ...
;             const bool last = (t == nt - 2);
;             const char* a1 = cA + (size_t)(t + 1) * kstep;
;             const char* a2 = last ? nA : cA + (size_t)(t + 2) * kstep; const char* b2 = last ? nB : cB + (size_t)(t + 2) * kstep;
;             const char* a3 = a2 + kstep; const char* b3 = b2 + kstep;
;             if (last && has_next) S.a_ready(nxt);
;             if constexpr (SP2) {
;             PG8_LDB(B0, 0, 0); PG8_LDB(B1, 0, 1); PG8_SCHED; PG8_LDA(At, 0, 0); PG8_STAGE(PG8_SA(1, 1), a1 + hstepA, voffA);
;             PG8_WAIT_V(8); PG8_WAIT_L(0); PG8_BAR; PG8_MMA(0, 0, At, B0); PG8_MMA(0, 1, At, B1); PG8_BAR; PG8_SCHED;
;             PG8_LDA(At, 0, 1); PG8_STAGE(PG8_SB(0, 0), b2, voffB); PG8_STAGE(PG8_SB(0, 1), b2 + hstepB, voffB); PG8_STAGE(PG8_SA(0, 0), a2, voffA);
;             PG8_WAIT_V(8); PG8_WAIT_L(0); PG8_BAR; PG8_MMA(1, 0, At, B0); PG8_MMA(1, 1, At, B1); PG8_BAR; PG8_SCHED;
.LBB0_176:
	s_add_i32 s67, s14, 2
	s_add_u32 s68, s12, 0xfff80080
	s_addc_u32 s15, s13, -1
	s_cmp_eq_u32 s61, s14
	s_cselect_b32 s15, s11, s15
	s_cselect_b32 s14, s35, s68
	s_cselect_b32 s69, s45, s43
	s_cselect_b32 s68, s44, s42
	ds_read_b128 v[66:69], v171
	ds_read_b128 v[74:77], v171 offset:1024
	ds_read_b128 v[82:85], v171 offset:2048
	ds_read_b128 v[86:89], v171 offset:3072
	ds_read_b128 v[154:157], v173
	ds_read_b128 v[158:161], v173 offset:1024
	ds_read_b128 v[174:177], v173 offset:2048
	ds_read_b128 v[178:181], v173 offset:3072
	s_add_i32 m0, s54, 0xc000
	ds_read_b128 v[202:205], v200
	ds_read_b128 v[206:209], v200 offset:1024
	ds_read_b128 v[210:213], v200 offset:2048
	ds_read_b128 v[214:217], v200 offset:3072
	ds_read_b128 v[228:231], v200 offset:4096
	ds_read_b128 v[232:235], v200 offset:5120
	ds_read_b128 v[236:239], v200 offset:6144
	ds_read_b128 v[240:243], v200 offset:7168
	global_load_lds_dwordx4 v170, s[12:13]
	s_add_i32 m0, s54, 0xe000
	s_nop 0
	global_load_lds_dwordx4 v172, s[12:13]
	s_waitcnt vmcnt(8) lgkmcnt(0)
	s_barrier
	v_mfma_f32_16x16x32_bf16 v[150:153], v[66:69], v[202:205], v[150:153]
	v_mfma_f32_16x16x32_bf16 v[146:149], v[82:85], v[202:205], v[146:149]
	v_mfma_f32_16x16x32_bf16 v[134:137], v[66:69], v[210:213], v[134:137]
	v_mfma_f32_16x16x32_bf16 v[130:133], v[82:85], v[210:213], v[130:133]
	v_mfma_f32_16x16x32_bf16 v[118:121], v[66:69], v[228:231], v[118:121]
	v_mfma_f32_16x16x32_bf16 v[114:117], v[82:85], v[228:231], v[114:117]
	v_mfma_f32_16x16x32_bf16 v[102:105], v[66:69], v[236:239], v[102:105]
	v_mfma_f32_16x16x32_bf16 v[98:101], v[82:85], v[236:239], v[98:101]
	v_mfma_f32_16x16x32_bf16 v[150:153], v[74:77], v[206:209], v[150:153]
	v_mfma_f32_16x16x32_bf16 v[146:149], v[86:89], v[206:209], v[146:149]
	v_mfma_f32_16x16x32_bf16 v[134:137], v[74:77], v[214:217], v[134:137]
	v_mfma_f32_16x16x32_bf16 v[130:133], v[86:89], v[214:217], v[130:133]
	v_mfma_f32_16x16x32_bf16 v[118:121], v[74:77], v[232:235], v[118:121]
	v_mfma_f32_16x16x32_bf16 v[114:117], v[86:89], v[232:235], v[114:117]
	v_mfma_f32_16x16x32_bf16 v[102:105], v[74:77], v[240:243], v[102:105]
	v_mfma_f32_16x16x32_bf16 v[98:101], v[86:89], v[240:243], v[98:101]
	v_mfma_f32_16x16x32_bf16 v[142:145], v[154:157], v[202:205], v[142:145]
	v_mfma_f32_16x16x32_bf16 v[138:141], v[174:177], v[202:205], v[138:141]
	v_mfma_f32_16x16x32_bf16 v[126:129], v[154:157], v[210:213], v[126:129]
	v_mfma_f32_16x16x32_bf16 v[122:125], v[174:177], v[210:213], v[122:125]
	v_mfma_f32_16x16x32_bf16 v[110:113], v[154:157], v[228:231], v[110:113]
	v_mfma_f32_16x16x32_bf16 v[106:109], v[174:177], v[228:231], v[106:109]
	v_mfma_f32_16x16x32_bf16 v[94:97], v[154:157], v[236:239], v[94:97]
	v_mfma_f32_16x16x32_bf16 v[90:93], v[174:177], v[236:239], v[90:93]
	v_mfma_f32_16x16x32_bf16 v[142:145], v[158:161], v[206:209], v[142:145]
	v_mfma_f32_16x16x32_bf16 v[138:141], v[178:181], v[206:209], v[138:141]
	v_mfma_f32_16x16x32_bf16 v[126:129], v[158:161], v[214:217], v[126:129]
	v_mfma_f32_16x16x32_bf16 v[122:125], v[178:181], v[214:217], v[122:125]
	v_mfma_f32_16x16x32_bf16 v[110:113], v[158:161], v[232:235], v[110:113]
	v_mfma_f32_16x16x32_bf16 v[106:109], v[178:181], v[232:235], v[106:109]
	v_mfma_f32_16x16x32_bf16 v[94:97], v[158:161], v[240:243], v[94:97]
	v_mfma_f32_16x16x32_bf16 v[90:93], v[178:181], v[240:243], v[90:93]
	s_barrier
	v_lshl_add_u64 v[218:219], s[68:69], 0, v[0:1]
	s_add_i32 m0, s53, 0x10000
	ds_read_b128 v[202:205], v200 offset:16384
	ds_read_b128 v[206:209], v200 offset:17408
	ds_read_b128 v[210:213], v200 offset:18432
	ds_read_b128 v[214:217], v200 offset:19456
	ds_read_b128 v[228:231], v200 offset:20480
	ds_read_b128 v[232:235], v200 offset:21504
	ds_read_b128 v[236:239], v200 offset:22528
	ds_read_b128 v[240:243], v200 offset:23552
	global_load_lds_dwordx4 v[218:219], off
	s_add_i32 m0, s53, 0x12000
	v_lshl_add_u64 v[244:245], s[68:69], 0, v[166:167]
	s_add_u32 s68, s68, s24
	s_addc_u32 s69, s69, s25
	s_add_i32 s70, s53, 0x14000
	global_load_lds_dwordx4 v[244:245], off
	s_mov_b32 m0, s70
	global_load_lds_dwordx4 v0, s[68:69]
	s_add_i32 m0, s70, 0x2000
	global_load_lds_dwordx4 v166, s[68:69]
	s_mov_b32 m0, s54
	global_load_lds_dwordx4 v162, s[14:15]
	s_mov_b32 m0, s55
	s_nop 0
	global_load_lds_dwordx4 v164, s[14:15]
	s_waitcnt vmcnt(8) lgkmcnt(0)
	s_barrier
	v_mfma_f32_16x16x32_bf16 v[78:81], v[66:69], v[202:205], v[78:81]
	v_mfma_f32_16x16x32_bf16 v[70:73], v[82:85], v[202:205], v[70:73]
	v_mfma_f32_16x16x32_bf16 v[46:49], v[66:69], v[210:213], v[46:49]
	v_mfma_f32_16x16x32_bf16 v[42:45], v[82:85], v[210:213], v[42:45]
	v_mfma_f32_16x16x32_bf16 v[30:33], v[66:69], v[228:231], v[30:33]
	v_mfma_f32_16x16x32_bf16 v[26:29], v[82:85], v[228:231], v[26:29]
	v_mfma_f32_16x16x32_bf16 v[14:17], v[66:69], v[236:239], v[14:17]
	v_mfma_f32_16x16x32_bf16 v[10:13], v[82:85], v[236:239], v[10:13]
	v_mfma_f32_16x16x32_bf16 v[78:81], v[74:77], v[206:209], v[78:81]
	v_mfma_f32_16x16x32_bf16 v[70:73], v[86:89], v[206:209], v[70:73]
	v_mfma_f32_16x16x32_bf16 v[46:49], v[74:77], v[214:217], v[46:49]
	v_mfma_f32_16x16x32_bf16 v[42:45], v[86:89], v[214:217], v[42:45]
	v_mfma_f32_16x16x32_bf16 v[30:33], v[74:77], v[232:235], v[30:33]
	v_mfma_f32_16x16x32_bf16 v[26:29], v[86:89], v[232:235], v[26:29]
	v_mfma_f32_16x16x32_bf16 v[14:17], v[74:77], v[240:243], v[14:17]
	v_mfma_f32_16x16x32_bf16 v[10:13], v[86:89], v[240:243], v[10:13]
	v_mfma_f32_16x16x32_bf16 v[60:63], v[154:157], v[202:205], v[62:65]
	v_mfma_f32_16x16x32_bf16 v[54:57], v[174:177], v[202:205], v[54:57]
	v_mfma_f32_16x16x32_bf16 v[38:41], v[154:157], v[210:213], v[38:41]
	v_mfma_f32_16x16x32_bf16 v[34:37], v[174:177], v[210:213], v[34:37]
	v_mfma_f32_16x16x32_bf16 v[22:25], v[154:157], v[228:231], v[22:25]
	v_mfma_f32_16x16x32_bf16 v[18:21], v[174:177], v[228:231], v[18:21]
	v_mfma_f32_16x16x32_bf16 v[6:9], v[154:157], v[236:239], v[6:9]
	v_mfma_f32_16x16x32_bf16 v[2:5], v[174:177], v[236:239], v[2:5]
	v_mfma_f32_16x16x32_bf16 v[60:63], v[158:161], v[206:209], v[60:63]
	v_mfma_f32_16x16x32_bf16 v[54:57], v[178:181], v[206:209], v[54:57]
	v_mfma_f32_16x16x32_bf16 v[38:41], v[158:161], v[214:217], v[38:41]
	v_mfma_f32_16x16x32_bf16 v[34:37], v[178:181], v[214:217], v[34:37]
	v_mfma_f32_16x16x32_bf16 v[22:25], v[158:161], v[232:235], v[22:25]
	v_mfma_f32_16x16x32_bf16 v[18:21], v[178:181], v[232:235], v[18:21]
	v_mfma_f32_16x16x32_bf16 v[6:9], v[158:161], v[240:243], v[6:9]
	v_mfma_f32_16x16x32_bf16 v[2:5], v[178:181], v[240:243], v[2:5]
	s_barrier
; #define PG8_STAGE(bufoff, gbase, voff) do { _Pragma("unroll") for (int _i = 0; _i < 2; ++_i) \
;         __builtin_amdgcn_global_load_lds((const unsigned*)((const char*)(gbase) + (voff)[_i]), (PG8_LAS unsigned*)(lds + (bufoff) + ldsw + _i * 8192), 16, 0, 0); } while (0)
; #define PG8_LDA(dst, b, h) do { _Pragma("unroll") for (int m = 0; m < 4; ++m) _Pragma("unroll") for (int k = 0; k < 2; ++k) dst[m][k] = *(const PG8_LAS bf16x8*)(lds + PG8_SA(b, h) + aoff + m * 2048 + k * 1024); } while (0)
; #define PG8_LDB(dst, b, h) do { _Pragma("unroll") for (int n = 0; n < 2; ++n) _Pragma("unroll") for (int k = 0; k < 2; ++k) dst[n][k] = *(const PG8_LAS bf16x8*)(lds + PG8_SB(b, h) + boff + n * 2048 + k * 1024); } while (0)
; #define PG8_MMA(ai, bj, At, Bt) do { __builtin_amdgcn_s_setprio(1); _Pragma("unroll") for (int m = 0; m < 4; ++m) _Pragma("unroll") for (int n = 0; n < 2; ++n) _Pragma("unroll") for (int k = 0; k < 2; ++k) \
;         acc[ai][bj][m][n] = __builtin_amdgcn_mfma_f32_16x16x32_bf16(Bt[n][k], At[m][k], acc[ai][bj][m][n], 0, 0, 0); __builtin_amdgcn_s_setprio(0); } while (0)
; #define PG8_WAIT_V(n) asm volatile("s_waitcnt vmcnt(" #n ")" ::: "memory")
; #define PG8_WAIT_L(n) asm volatile("s_waitcnt lgkmcnt(" #n ")" ::: "memory")
; template <class Epi, class Sched, bool ALIGN_EPI = false, bool SP2 = false>
; __device__ __forceinline__ void gemm_phase(PG8_LAS unsigned char* lds, const Gemm g, const Sched& S, const Epi& E, const int wv) {
;     ...
;         for (int t = 0; t < nt; t += 2) {
;             const bool last = (t == nt - 2);
;             const char* a1 = cA + (size_t)(t + 1) * kstep;
;             const char* a2 = last ? nA : cA + (size_t)(t + 2) * kstep; const char* b2 = last ? nB : cB + (size_t)(t + 2) * kstep;
;             const char* a3 = a2 + kstep; const char* b3 = b2 + kstep;
;             if (last && has_next) S.a_ready(nxt);
;     ...
;             PG8_LDB(B0, 1, 0); PG8_LDB(B1, 1, 1); PG8_SCHED; PG8_LDA(At, 1, 0); PG8_STAGE(PG8_SA(0, 1), a2 + hstepA, voffA);
;             PG8_WAIT_V(8); PG8_WAIT_L(0); PG8_BAR; PG8_MMA(0, 0, At, B0); PG8_MMA(0, 1, At, B1); PG8_BAR; PG8_SCHED;
;             PG8_LDA(At, 1, 1); PG8_STAGE(PG8_SB(1, 0), b3, voffB); PG8_STAGE(PG8_SB(1, 1), b3 + hstepB, voffB); PG8_STAGE(PG8_SA(1, 0), a3, voffA);
;             PG8_WAIT_V(8); PG8_WAIT_L(0); PG8_BAR; PG8_MMA(1, 0, At, B0); PG8_MMA(1, 1, At, B1); PG8_BAR; PG8_SCHED;
	ds_read_b128 v[64:67], v201
	ds_read_b128 v[74:77], v201 offset:1024
	ds_read_b128 v[82:85], v201 offset:2048
	ds_read_b128 v[86:89], v201 offset:3072
	ds_read_b128 v[154:157], v227
	ds_read_b128 v[158:161], v227 offset:1024
	ds_read_b128 v[174:177], v227 offset:2048
	ds_read_b128 v[178:181], v227 offset:3072
	s_mov_b32 m0, s56
	ds_read_b128 v[202:205], v200 offset:32768
	ds_read_b128 v[206:209], v200 offset:33792
	ds_read_b128 v[210:213], v200 offset:34816
	ds_read_b128 v[214:217], v200 offset:35840
	ds_read_b128 v[228:231], v200 offset:36864
	ds_read_b128 v[232:235], v200 offset:37888
	ds_read_b128 v[236:239], v200 offset:38912
	ds_read_b128 v[240:243], v200 offset:39936
	global_load_lds_dwordx4 v59, s[14:15]
	s_mov_b32 m0, s57
	s_nop 0
	global_load_lds_dwordx4 v246, s[14:15]
	s_waitcnt vmcnt(8) lgkmcnt(0)
	s_barrier
	v_mfma_f32_16x16x32_bf16 v[150:153], v[64:67], v[202:205], v[150:153]
	v_mfma_f32_16x16x32_bf16 v[146:149], v[82:85], v[202:205], v[146:149]
	v_mfma_f32_16x16x32_bf16 v[134:137], v[64:67], v[210:213], v[134:137]
	v_mfma_f32_16x16x32_bf16 v[130:133], v[82:85], v[210:213], v[130:133]
	v_mfma_f32_16x16x32_bf16 v[118:121], v[64:67], v[228:231], v[118:121]
	v_mfma_f32_16x16x32_bf16 v[114:117], v[82:85], v[228:231], v[114:117]
	v_mfma_f32_16x16x32_bf16 v[102:105], v[64:67], v[236:239], v[102:105]
	v_mfma_f32_16x16x32_bf16 v[98:101], v[82:85], v[236:239], v[98:101]
	v_mfma_f32_16x16x32_bf16 v[150:153], v[74:77], v[206:209], v[150:153]
	v_mfma_f32_16x16x32_bf16 v[146:149], v[86:89], v[206:209], v[146:149]
	v_mfma_f32_16x16x32_bf16 v[134:137], v[74:77], v[214:217], v[134:137]
	v_mfma_f32_16x16x32_bf16 v[130:133], v[86:89], v[214:217], v[130:133]
	v_mfma_f32_16x16x32_bf16 v[118:121], v[74:77], v[232:235], v[118:121]
	v_mfma_f32_16x16x32_bf16 v[114:117], v[86:89], v[232:235], v[114:117]
	v_mfma_f32_16x16x32_bf16 v[102:105], v[74:77], v[240:243], v[102:105]
	v_mfma_f32_16x16x32_bf16 v[98:101], v[86:89], v[240:243], v[98:101]
	v_mfma_f32_16x16x32_bf16 v[142:145], v[154:157], v[202:205], v[142:145]
	v_mfma_f32_16x16x32_bf16 v[138:141], v[174:177], v[202:205], v[138:141]
	v_mfma_f32_16x16x32_bf16 v[126:129], v[154:157], v[210:213], v[126:129]
	v_mfma_f32_16x16x32_bf16 v[122:125], v[174:177], v[210:213], v[122:125]
	v_mfma_f32_16x16x32_bf16 v[110:113], v[154:157], v[228:231], v[110:113]
	v_mfma_f32_16x16x32_bf16 v[106:109], v[174:177], v[228:231], v[106:109]
	v_mfma_f32_16x16x32_bf16 v[94:97], v[154:157], v[236:239], v[94:97]
	v_mfma_f32_16x16x32_bf16 v[90:93], v[174:177], v[236:239], v[90:93]
	v_mfma_f32_16x16x32_bf16 v[142:145], v[158:161], v[206:209], v[142:145]
	v_mfma_f32_16x16x32_bf16 v[138:141], v[178:181], v[206:209], v[138:141]
	v_mfma_f32_16x16x32_bf16 v[126:129], v[158:161], v[214:217], v[126:129]
	v_mfma_f32_16x16x32_bf16 v[122:125], v[178:181], v[214:217], v[122:125]
	v_mfma_f32_16x16x32_bf16 v[110:113], v[158:161], v[232:235], v[110:113]
	v_mfma_f32_16x16x32_bf16 v[106:109], v[178:181], v[232:235], v[106:109]
	v_mfma_f32_16x16x32_bf16 v[94:97], v[158:161], v[240:243], v[94:97]
	v_mfma_f32_16x16x32_bf16 v[90:93], v[178:181], v[240:243], v[90:93]
	s_barrier
	s_add_i32 m0, s53, 0x17f80
	ds_read_b128 v[202:205], v200 offset:49152
	ds_read_b128 v[206:209], v200 offset:50176
	ds_read_b128 v[210:213], v200 offset:51200
	ds_read_b128 v[214:217], v200 offset:52224
	ds_read_b128 v[228:231], v200 offset:53248
	ds_read_b128 v[232:235], v200 offset:54272
	ds_read_b128 v[236:239], v200 offset:55296
	ds_read_b128 v[240:243], v200 offset:56320
	global_load_lds_dwordx4 v[218:219], off offset:128
	s_add_i32 m0, s53, 0x19f80
	global_load_lds_dwordx4 v[244:245], off offset:128
	s_add_i32 m0, s53, 0x1bf80
	s_nop 0
	global_load_lds_dwordx4 v0, s[68:69] offset:128
	s_add_i32 m0, s53, 0x1df80
	s_nop 0
	global_load_lds_dwordx4 v166, s[68:69] offset:128
	s_add_i32 m0, s58, 0xffffff80
	s_nop 0
	global_load_lds_dwordx4 v162, s[14:15] offset:128
	s_add_i32 m0, s59, 0xffffff80
	s_nop 0
	global_load_lds_dwordx4 v164, s[14:15] offset:128
	s_waitcnt vmcnt(8) lgkmcnt(0)
	s_barrier
	v_mfma_f32_16x16x32_bf16 v[78:81], v[64:67], v[202:205], v[78:81]
	v_mfma_f32_16x16x32_bf16 v[68:71], v[82:85], v[202:205], v[70:73]
	v_mfma_f32_16x16x32_bf16 v[46:49], v[64:67], v[210:213], v[46:49]
	v_mfma_f32_16x16x32_bf16 v[42:45], v[82:85], v[210:213], v[42:45]
	v_mfma_f32_16x16x32_bf16 v[30:33], v[64:67], v[228:231], v[30:33]
	v_mfma_f32_16x16x32_bf16 v[26:29], v[82:85], v[228:231], v[26:29]
	v_mfma_f32_16x16x32_bf16 v[14:17], v[64:67], v[236:239], v[14:17]
	v_mfma_f32_16x16x32_bf16 v[10:13], v[82:85], v[236:239], v[10:13]
	v_mfma_f32_16x16x32_bf16 v[78:81], v[74:77], v[206:209], v[78:81]
	v_mfma_f32_16x16x32_bf16 v[70:73], v[86:89], v[206:209], v[68:71]
	v_mfma_f32_16x16x32_bf16 v[46:49], v[74:77], v[214:217], v[46:49]
	v_mfma_f32_16x16x32_bf16 v[42:45], v[86:89], v[214:217], v[42:45]
	v_mfma_f32_16x16x32_bf16 v[30:33], v[74:77], v[232:235], v[30:33]
	v_mfma_f32_16x16x32_bf16 v[26:29], v[86:89], v[232:235], v[26:29]
	v_mfma_f32_16x16x32_bf16 v[14:17], v[74:77], v[240:243], v[14:17]
	v_mfma_f32_16x16x32_bf16 v[10:13], v[86:89], v[240:243], v[10:13]
	v_mfma_f32_16x16x32_bf16 v[60:63], v[154:157], v[202:205], v[60:63]
	v_mfma_f32_16x16x32_bf16 v[54:57], v[174:177], v[202:205], v[54:57]
	v_mfma_f32_16x16x32_bf16 v[38:41], v[154:157], v[210:213], v[38:41]
	v_mfma_f32_16x16x32_bf16 v[34:37], v[174:177], v[210:213], v[34:37]
	v_mfma_f32_16x16x32_bf16 v[22:25], v[154:157], v[228:231], v[22:25]
	v_mfma_f32_16x16x32_bf16 v[18:21], v[174:177], v[228:231], v[18:21]
	v_mfma_f32_16x16x32_bf16 v[6:9], v[154:157], v[236:239], v[6:9]
	v_mfma_f32_16x16x32_bf16 v[2:5], v[174:177], v[236:239], v[2:5]
	v_mfma_f32_16x16x32_bf16 v[62:65], v[158:161], v[206:209], v[60:63]
	v_mfma_f32_16x16x32_bf16 v[54:57], v[178:181], v[206:209], v[54:57]
	v_mfma_f32_16x16x32_bf16 v[38:41], v[158:161], v[214:217], v[38:41]
	v_mfma_f32_16x16x32_bf16 v[34:37], v[178:181], v[214:217], v[34:37]
	v_mfma_f32_16x16x32_bf16 v[22:25], v[158:161], v[232:235], v[22:25]
	v_mfma_f32_16x16x32_bf16 v[18:21], v[178:181], v[232:235], v[18:21]
	v_mfma_f32_16x16x32_bf16 v[6:9], v[158:161], v[240:243], v[6:9]
	v_mfma_f32_16x16x32_bf16 v[2:5], v[178:181], v[240:243], v[2:5]
	s_barrier
	s_add_u32 s12, s12, 0x100
	s_addc_u32 s13, s13, 0
	s_add_u32 s42, s42, 0x100
	s_addc_u32 s43, s43, 0
	s_cmp_ge_i32 s67, s60
	s_mov_b32 s14, s67
	s_cbranch_scc0 .LBB0_176
	s_movk_i32 s68, 0x4000
	s_movk_i32 s69, 0x6000
	s_mov_b32 s70, 0x18000
	s_mov_b32 s71, 0x3f317217

; #define PG8_STAGE(bufoff, gbase, voff) do { _Pragma("unroll") for (int _i = 0; _i < 2; ++_i) \
;         __builtin_amdgcn_global_load_lds((const unsigned*)((const char*)(gbase) + (voff)[_i]), (PG8_LAS unsigned*)(lds + (bufoff) + ldsw + _i * 8192), 16, 0, 0); } while (0)
; #define PG8_LDA(dst, b, h) do { _Pragma("unroll") for (int m = 0; m < 4; ++m) _Pragma("unroll") for (int k = 0; k < 2; ++k) dst[m][k] = *(const PG8_LAS bf16x8*)(lds + PG8_SA(b, h) + aoff + m * 2048 + k * 1024); } while (0)
; #define PG8_LDB(dst, b, h) do { _Pragma("unroll") for (int n = 0; n < 2; ++n) _Pragma("unroll") for (int k = 0; k < 2; ++k) dst[n][k] = *(const PG8_LAS bf16x8*)(lds + PG8_SB(b, h) + boff + n * 2048 + k * 1024); } while (0)
; #define PG8_MMA(ai, bj, At, Bt) do { __builtin_amdgcn_s_setprio(1); _Pragma("unroll") for (int m = 0; m < 4; ++m) _Pragma("unroll") for (int n = 0; n < 2; ++n) _Pragma("unroll") for (int k = 0; k < 2; ++k) \
;         acc[ai][bj][m][n] = __builtin_amdgcn_mfma_f32_16x16x32_bf16(Bt[n][k], At[m][k], acc[ai][bj][m][n], 0, 0, 0); __builtin_amdgcn_s_setprio(0); } while (0)
; #define PG8_WAIT_V(n) asm volatile("s_waitcnt vmcnt(" #n ")" ::: "memory")
; #define PG8_WAIT_L(n) asm volatile("s_waitcnt lgkmcnt(" #n ")" ::: "memory")
; template <class Epi, class Sched, bool ALIGN_EPI = false, bool SP2 = false>
; __device__ __forceinline__ void gemm_phase(PG8_LAS unsigned char* lds, const Gemm g, const Sched& S, const Epi& E, const int wv) {
;     ...
;             const bool last = (t == nt - 2);
;             const char* a1 = cA + (size_t)(t + 1) * kstep;
;             const char* a2 = last ? nA : cA + (size_t)(t + 2) * kstep; const char* b2 = last ? nB : cB + (size_t)(t + 2) * kstep;
;             const char* a3 = a2 + kstep; const char* b3 = b2 + kstep;
;             if (last && has_next) S.a_ready(nxt);
;             if constexpr (SP2) {
;             PG8_LDB(B0, 0, 0); PG8_LDB(B1, 0, 1); PG8_SCHED; PG8_LDA(At, 0, 0); PG8_STAGE(PG8_SA(1, 1), a1 + hstepA, voffA);
;             PG8_WAIT_V(8); PG8_WAIT_L(0); PG8_BAR; PG8_MMA(0, 0, At, B0); PG8_MMA(0, 1, At, B1); PG8_BAR; PG8_SCHED;
;             PG8_LDA(At, 0, 1); PG8_STAGE(PG8_SB(0, 0), b2, voffB); PG8_STAGE(PG8_SB(0, 1), b2 + hstepB, voffB); PG8_STAGE(PG8_SA(0, 0), a2, voffA);
;             PG8_WAIT_V(8); PG8_WAIT_L(0); PG8_BAR; PG8_MMA(1, 0, At, B0); PG8_MMA(1, 1, At, B1); PG8_BAR; PG8_SCHED;
.LBB0_809:
	s_add_i32 s52, s46, 2
	s_add_u32 s14, s48, 0x100
	s_addc_u32 s15, s49, 0
	s_cmp_eq_u32 s71, s46
	s_cselect_b32 s47, s11, s15
	s_cselect_b32 s46, s13, s14
	s_cselect_b32 s77, s87, s51
	s_cselect_b32 s76, s86, s35
	ds_read_b128 v[138:141], v192
	ds_read_b128 v[142:145], v192 offset:1024
	ds_read_b128 v[146:149], v192 offset:2048
	ds_read_b128 v[150:153], v192 offset:3072
	ds_read_b128 v[154:157], v193
	ds_read_b128 v[158:161], v193 offset:1024
	ds_read_b128 v[162:165], v193 offset:2048
	ds_read_b128 v[166:169], v193 offset:3072
	s_add_i32 m0, s63, 0xc000
	ds_read_b128 v[194:197], v211
	ds_read_b128 v[198:201], v211 offset:1024
	ds_read_b128 v[202:205], v211 offset:2048
	ds_read_b128 v[214:217], v211 offset:3072
	ds_read_b128 v[228:231], v211 offset:4096
	ds_read_b128 v[232:235], v211 offset:5120
	ds_read_b128 v[236:239], v211 offset:6144
	ds_read_b128 v[240:243], v211 offset:7168
	global_load_lds_dwordx4 v182, s[48:49]
	v_lshl_add_u64 v[190:191], s[48:49], 0, v[184:185]
	s_add_i32 m0, s63, 0xe000
	s_nop 0
	global_load_lds_dwordx4 v[190:191], off
	s_waitcnt vmcnt(8) lgkmcnt(0)
	s_barrier
	v_mfma_f32_16x16x32_bf16 v[118:121], v[138:141], v[194:197], v[118:121]
	v_mfma_f32_16x16x32_bf16 v[46:49], v[146:149], v[194:197], v[46:49]
	v_mfma_f32_16x16x32_bf16 v[110:113], v[138:141], v[202:205], v[110:113]
	v_mfma_f32_16x16x32_bf16 v[38:41], v[146:149], v[202:205], v[38:41]
	v_mfma_f32_16x16x32_bf16 v[134:137], v[138:141], v[228:231], v[134:137]
	v_mfma_f32_16x16x32_bf16 v[62:65], v[146:149], v[228:231], v[62:65]
	v_mfma_f32_16x16x32_bf16 v[130:133], v[138:141], v[236:239], v[130:133]
	v_mfma_f32_16x16x32_bf16 v[58:61], v[146:149], v[236:239], v[58:61]
	v_mfma_f32_16x16x32_bf16 v[118:121], v[142:145], v[198:201], v[118:121]
	v_mfma_f32_16x16x32_bf16 v[46:49], v[150:153], v[198:201], v[46:49]
	v_mfma_f32_16x16x32_bf16 v[110:113], v[142:145], v[214:217], v[110:113]
	v_mfma_f32_16x16x32_bf16 v[38:41], v[150:153], v[214:217], v[38:41]
	v_mfma_f32_16x16x32_bf16 v[134:137], v[142:145], v[232:235], v[134:137]
	v_mfma_f32_16x16x32_bf16 v[62:65], v[150:153], v[232:235], v[62:65]
	v_mfma_f32_16x16x32_bf16 v[130:133], v[142:145], v[240:243], v[130:133]
	v_mfma_f32_16x16x32_bf16 v[58:61], v[150:153], v[240:243], v[58:61]
	v_mfma_f32_16x16x32_bf16 v[114:117], v[154:157], v[194:197], v[114:117]
	v_mfma_f32_16x16x32_bf16 v[42:45], v[162:165], v[194:197], v[42:45]
	v_mfma_f32_16x16x32_bf16 v[106:109], v[154:157], v[202:205], v[106:109]
	v_mfma_f32_16x16x32_bf16 v[34:37], v[162:165], v[202:205], v[34:37]
	v_mfma_f32_16x16x32_bf16 v[126:129], v[154:157], v[228:231], v[126:129]
	v_mfma_f32_16x16x32_bf16 v[54:57], v[162:165], v[228:231], v[54:57]
	v_mfma_f32_16x16x32_bf16 v[122:125], v[154:157], v[236:239], v[122:125]
	v_mfma_f32_16x16x32_bf16 v[50:53], v[162:165], v[236:239], v[50:53]
	v_mfma_f32_16x16x32_bf16 v[114:117], v[158:161], v[198:201], v[114:117]
	v_mfma_f32_16x16x32_bf16 v[42:45], v[166:169], v[198:201], v[42:45]
	v_mfma_f32_16x16x32_bf16 v[106:109], v[158:161], v[214:217], v[106:109]
	v_mfma_f32_16x16x32_bf16 v[34:37], v[166:169], v[214:217], v[34:37]
	v_mfma_f32_16x16x32_bf16 v[126:129], v[158:161], v[232:235], v[126:129]
	v_mfma_f32_16x16x32_bf16 v[54:57], v[166:169], v[232:235], v[54:57]
	v_mfma_f32_16x16x32_bf16 v[122:125], v[158:161], v[240:243], v[122:125]
	v_mfma_f32_16x16x32_bf16 v[50:53], v[166:169], v[240:243], v[50:53]
	s_barrier
	s_add_i32 m0, s62, 0x10000
	ds_read_b128 v[194:197], v211 offset:16384
	ds_read_b128 v[198:201], v211 offset:17408
	ds_read_b128 v[202:205], v211 offset:18432
	ds_read_b128 v[214:217], v211 offset:19456
	ds_read_b128 v[228:231], v211 offset:20480
	ds_read_b128 v[232:235], v211 offset:21504
	ds_read_b128 v[236:239], v211 offset:22528
	ds_read_b128 v[240:243], v211 offset:23552
	global_load_lds_dwordx4 v0, s[76:77]
	s_add_i32 m0, s62, 0x12000
	s_add_u32 s48, s76, s16
	s_addc_u32 s49, s77, s17
	s_add_i32 s53, s62, 0x14000
	global_load_lds_dwordx4 v174, s[76:77]
	s_mov_b32 m0, s53
	global_load_lds_dwordx4 v0, s[48:49]
	s_add_i32 m0, s53, 0x2000
	global_load_lds_dwordx4 v174, s[48:49]
	s_mov_b32 m0, s63
	global_load_lds_dwordx4 v170, s[46:47]
	s_mov_b32 m0, s64
	s_nop 0
	global_load_lds_dwordx4 v172, s[46:47]
	s_waitcnt vmcnt(8) lgkmcnt(0)
	s_barrier
	v_mfma_f32_16x16x32_bf16 v[86:89], v[138:141], v[194:197], v[86:89]
	v_mfma_f32_16x16x32_bf16 v[14:17], v[146:149], v[194:197], v[14:17]
	v_mfma_f32_16x16x32_bf16 v[70:73], v[138:141], v[202:205], v[70:73]
	v_mfma_f32_16x16x32_bf16 v[6:9], v[146:149], v[202:205], v[6:9]
	v_mfma_f32_16x16x32_bf16 v[102:105], v[138:141], v[228:231], v[102:105]
	v_mfma_f32_16x16x32_bf16 v[30:33], v[146:149], v[228:231], v[30:33]
	v_mfma_f32_16x16x32_bf16 v[98:101], v[138:141], v[236:239], v[98:101]
	v_mfma_f32_16x16x32_bf16 v[26:29], v[146:149], v[236:239], v[26:29]
	v_mfma_f32_16x16x32_bf16 v[86:89], v[142:145], v[198:201], v[86:89]
	v_mfma_f32_16x16x32_bf16 v[14:17], v[150:153], v[198:201], v[14:17]
	v_mfma_f32_16x16x32_bf16 v[70:73], v[142:145], v[214:217], v[70:73]
	v_mfma_f32_16x16x32_bf16 v[6:9], v[150:153], v[214:217], v[6:9]
	v_mfma_f32_16x16x32_bf16 v[102:105], v[142:145], v[232:235], v[102:105]
	v_mfma_f32_16x16x32_bf16 v[30:33], v[150:153], v[232:235], v[30:33]
	v_mfma_f32_16x16x32_bf16 v[98:101], v[142:145], v[240:243], v[98:101]
	v_mfma_f32_16x16x32_bf16 v[26:29], v[150:153], v[240:243], v[26:29]
	v_mfma_f32_16x16x32_bf16 v[82:85], v[154:157], v[194:197], v[82:85]
	v_mfma_f32_16x16x32_bf16 v[10:13], v[162:165], v[194:197], v[10:13]
	v_mfma_f32_16x16x32_bf16 v[66:69], v[154:157], v[202:205], v[66:69]
	v_mfma_f32_16x16x32_bf16 v[2:5], v[162:165], v[202:205], v[2:5]
	v_mfma_f32_16x16x32_bf16 v[94:97], v[154:157], v[228:231], v[94:97]
	v_mfma_f32_16x16x32_bf16 v[22:25], v[162:165], v[228:231], v[22:25]
	v_mfma_f32_16x16x32_bf16 v[90:93], v[154:157], v[236:239], v[90:93]
	v_mfma_f32_16x16x32_bf16 v[18:21], v[162:165], v[236:239], v[18:21]
	v_mfma_f32_16x16x32_bf16 v[82:85], v[158:161], v[198:201], v[82:85]
	v_mfma_f32_16x16x32_bf16 v[10:13], v[166:169], v[198:201], v[10:13]
	v_mfma_f32_16x16x32_bf16 v[66:69], v[158:161], v[214:217], v[66:69]
	v_mfma_f32_16x16x32_bf16 v[2:5], v[166:169], v[214:217], v[2:5]
	v_mfma_f32_16x16x32_bf16 v[94:97], v[158:161], v[232:235], v[94:97]
	v_mfma_f32_16x16x32_bf16 v[22:25], v[166:169], v[232:235], v[22:25]
	v_mfma_f32_16x16x32_bf16 v[90:93], v[158:161], v[240:243], v[90:93]
	v_mfma_f32_16x16x32_bf16 v[18:21], v[166:169], v[240:243], v[18:21]
	s_barrier
; #define PG8_STAGE(bufoff, gbase, voff) do { _Pragma("unroll") for (int _i = 0; _i < 2; ++_i) \
;         __builtin_amdgcn_global_load_lds((const unsigned*)((const char*)(gbase) + (voff)[_i]), (PG8_LAS unsigned*)(lds + (bufoff) + ldsw + _i * 8192), 16, 0, 0); } while (0)
; #define PG8_LDA(dst, b, h) do { _Pragma("unroll") for (int m = 0; m < 4; ++m) _Pragma("unroll") for (int k = 0; k < 2; ++k) dst[m][k] = *(const PG8_LAS bf16x8*)(lds + PG8_SA(b, h) + aoff + m * 2048 + k * 1024); } while (0)
; #define PG8_LDB(dst, b, h) do { _Pragma("unroll") for (int n = 0; n < 2; ++n) _Pragma("unroll") for (int k = 0; k < 2; ++k) dst[n][k] = *(const PG8_LAS bf16x8*)(lds + PG8_SB(b, h) + boff + n * 2048 + k * 1024); } while (0)
; #define PG8_MMA(ai, bj, At, Bt) do { __builtin_amdgcn_s_setprio(1); _Pragma("unroll") for (int m = 0; m < 4; ++m) _Pragma("unroll") for (int n = 0; n < 2; ++n) _Pragma("unroll") for (int k = 0; k < 2; ++k) \
;         acc[ai][bj][m][n] = __builtin_amdgcn_mfma_f32_16x16x32_bf16(Bt[n][k], At[m][k], acc[ai][bj][m][n], 0, 0, 0); __builtin_amdgcn_s_setprio(0); } while (0)
; #define PG8_WAIT_V(n) asm volatile("s_waitcnt vmcnt(" #n ")" ::: "memory")
; #define PG8_WAIT_L(n) asm volatile("s_waitcnt lgkmcnt(" #n ")" ::: "memory")
; template <class Epi, class Sched, bool ALIGN_EPI = false, bool SP2 = false>
; __device__ __forceinline__ void gemm_phase(PG8_LAS unsigned char* lds, const Gemm g, const Sched& S, const Epi& E, const int wv) {
;     ...
;         for (int t = 0; t < nt; t += 2) {
;             const bool last = (t == nt - 2);
;             const char* a1 = cA + (size_t)(t + 1) * kstep;
;             const char* a2 = last ? nA : cA + (size_t)(t + 2) * kstep; const char* b2 = last ? nB : cB + (size_t)(t + 2) * kstep;
;             const char* a3 = a2 + kstep; const char* b3 = b2 + kstep;
;             if (last && has_next) S.a_ready(nxt);
;     ...
;             PG8_LDB(B0, 1, 0); PG8_LDB(B1, 1, 1); PG8_SCHED; PG8_LDA(At, 1, 0); PG8_STAGE(PG8_SA(0, 1), a2 + hstepA, voffA);
;             PG8_WAIT_V(8); PG8_WAIT_L(0); PG8_BAR; PG8_MMA(0, 0, At, B0); PG8_MMA(0, 1, At, B1); PG8_BAR; PG8_SCHED;
;             PG8_LDA(At, 1, 1); PG8_STAGE(PG8_SB(1, 0), b3, voffB); PG8_STAGE(PG8_SB(1, 1), b3 + hstepB, voffB); PG8_STAGE(PG8_SA(1, 0), a3, voffA);
;             PG8_WAIT_V(8); PG8_WAIT_L(0); PG8_BAR; PG8_MMA(1, 0, At, B0); PG8_MMA(1, 1, At, B1); PG8_BAR; PG8_SCHED;
	ds_read_b128 v[138:141], v213
	ds_read_b128 v[142:145], v213 offset:1024
	ds_read_b128 v[146:149], v213 offset:2048
	ds_read_b128 v[150:153], v213 offset:3072
	ds_read_b128 v[154:157], v227
	ds_read_b128 v[158:161], v227 offset:1024
	ds_read_b128 v[162:165], v227 offset:2048
	ds_read_b128 v[166:169], v227 offset:3072
	s_mov_b32 m0, s65
	ds_read_b128 v[194:197], v211 offset:32768
	ds_read_b128 v[198:201], v211 offset:33792
	ds_read_b128 v[202:205], v211 offset:34816
	ds_read_b128 v[214:217], v211 offset:35840
	ds_read_b128 v[228:231], v211 offset:36864
	ds_read_b128 v[232:235], v211 offset:37888
	ds_read_b128 v[236:239], v211 offset:38912
	ds_read_b128 v[240:243], v211 offset:39936
	global_load_lds_dwordx4 v218, s[46:47]
	s_mov_b32 m0, s66
	s_nop 0
	global_load_lds_dwordx4 v219, s[46:47]
	s_waitcnt vmcnt(8) lgkmcnt(0)
	s_barrier
	v_mfma_f32_16x16x32_bf16 v[118:121], v[138:141], v[194:197], v[118:121]
	v_mfma_f32_16x16x32_bf16 v[46:49], v[146:149], v[194:197], v[46:49]
	v_mfma_f32_16x16x32_bf16 v[110:113], v[138:141], v[202:205], v[110:113]
	v_mfma_f32_16x16x32_bf16 v[38:41], v[146:149], v[202:205], v[38:41]
	v_mfma_f32_16x16x32_bf16 v[134:137], v[138:141], v[228:231], v[134:137]
	v_mfma_f32_16x16x32_bf16 v[62:65], v[146:149], v[228:231], v[62:65]
	v_mfma_f32_16x16x32_bf16 v[130:133], v[138:141], v[236:239], v[130:133]
	v_mfma_f32_16x16x32_bf16 v[58:61], v[146:149], v[236:239], v[58:61]
	v_mfma_f32_16x16x32_bf16 v[118:121], v[142:145], v[198:201], v[118:121]
	v_mfma_f32_16x16x32_bf16 v[46:49], v[150:153], v[198:201], v[46:49]
	v_mfma_f32_16x16x32_bf16 v[110:113], v[142:145], v[214:217], v[110:113]
	v_mfma_f32_16x16x32_bf16 v[38:41], v[150:153], v[214:217], v[38:41]
	v_mfma_f32_16x16x32_bf16 v[134:137], v[142:145], v[232:235], v[134:137]
	v_mfma_f32_16x16x32_bf16 v[62:65], v[150:153], v[232:235], v[62:65]
	v_mfma_f32_16x16x32_bf16 v[130:133], v[142:145], v[240:243], v[130:133]
	v_mfma_f32_16x16x32_bf16 v[58:61], v[150:153], v[240:243], v[58:61]
	v_mfma_f32_16x16x32_bf16 v[114:117], v[154:157], v[194:197], v[114:117]
	v_mfma_f32_16x16x32_bf16 v[42:45], v[162:165], v[194:197], v[42:45]
	v_mfma_f32_16x16x32_bf16 v[106:109], v[154:157], v[202:205], v[106:109]
	v_mfma_f32_16x16x32_bf16 v[34:37], v[162:165], v[202:205], v[34:37]
	v_mfma_f32_16x16x32_bf16 v[126:129], v[154:157], v[228:231], v[126:129]
	v_mfma_f32_16x16x32_bf16 v[54:57], v[162:165], v[228:231], v[54:57]
	v_mfma_f32_16x16x32_bf16 v[122:125], v[154:157], v[236:239], v[122:125]
	v_mfma_f32_16x16x32_bf16 v[50:53], v[162:165], v[236:239], v[50:53]
	v_mfma_f32_16x16x32_bf16 v[114:117], v[158:161], v[198:201], v[114:117]
	v_mfma_f32_16x16x32_bf16 v[42:45], v[166:169], v[198:201], v[42:45]
	v_mfma_f32_16x16x32_bf16 v[106:109], v[158:161], v[214:217], v[106:109]
	v_mfma_f32_16x16x32_bf16 v[34:37], v[166:169], v[214:217], v[34:37]
	v_mfma_f32_16x16x32_bf16 v[126:129], v[158:161], v[232:235], v[126:129]
	v_mfma_f32_16x16x32_bf16 v[54:57], v[166:169], v[232:235], v[54:57]
	v_mfma_f32_16x16x32_bf16 v[122:125], v[158:161], v[240:243], v[122:125]
	v_mfma_f32_16x16x32_bf16 v[50:53], v[166:169], v[240:243], v[50:53]
	s_barrier
	s_add_i32 m0, s62, 0x17f80
	ds_read_b128 v[194:197], v211 offset:49152
	ds_read_b128 v[198:201], v211 offset:50176
	ds_read_b128 v[202:205], v211 offset:51200
	ds_read_b128 v[214:217], v211 offset:52224
	ds_read_b128 v[228:231], v211 offset:53248
	ds_read_b128 v[232:235], v211 offset:54272
	ds_read_b128 v[236:239], v211 offset:55296
	ds_read_b128 v[240:243], v211 offset:56320
	global_load_lds_dwordx4 v0, s[76:77] offset:128
	s_add_i32 m0, s62, 0x19f80
	global_load_lds_dwordx4 v174, s[76:77] offset:128
	s_add_i32 m0, s62, 0x1bf80
	s_nop 0
	global_load_lds_dwordx4 v0, s[48:49] offset:128
	s_add_i32 m0, s62, 0x1df80
	s_nop 0
	global_load_lds_dwordx4 v174, s[48:49] offset:128
	s_add_i32 m0, s69, 0xffffff80
	s_nop 0
	global_load_lds_dwordx4 v170, s[46:47] offset:128
	s_add_i32 m0, s70, 0xffffff80
	s_nop 0
	global_load_lds_dwordx4 v172, s[46:47] offset:128
	s_waitcnt vmcnt(8) lgkmcnt(0)
	s_barrier
	v_mfma_f32_16x16x32_bf16 v[86:89], v[138:141], v[194:197], v[86:89]
	v_mfma_f32_16x16x32_bf16 v[14:17], v[146:149], v[194:197], v[14:17]
	v_mfma_f32_16x16x32_bf16 v[70:73], v[138:141], v[202:205], v[70:73]
	v_mfma_f32_16x16x32_bf16 v[6:9], v[146:149], v[202:205], v[6:9]
	v_mfma_f32_16x16x32_bf16 v[102:105], v[138:141], v[228:231], v[102:105]
	v_mfma_f32_16x16x32_bf16 v[30:33], v[146:149], v[228:231], v[30:33]
	v_mfma_f32_16x16x32_bf16 v[98:101], v[138:141], v[236:239], v[98:101]
	v_mfma_f32_16x16x32_bf16 v[26:29], v[146:149], v[236:239], v[26:29]
	v_mfma_f32_16x16x32_bf16 v[86:89], v[142:145], v[198:201], v[86:89]
	v_mfma_f32_16x16x32_bf16 v[14:17], v[150:153], v[198:201], v[14:17]
	v_mfma_f32_16x16x32_bf16 v[70:73], v[142:145], v[214:217], v[70:73]
	v_mfma_f32_16x16x32_bf16 v[6:9], v[150:153], v[214:217], v[6:9]
	v_mfma_f32_16x16x32_bf16 v[102:105], v[142:145], v[232:235], v[102:105]
	v_mfma_f32_16x16x32_bf16 v[30:33], v[150:153], v[232:235], v[30:33]
	v_mfma_f32_16x16x32_bf16 v[98:101], v[142:145], v[240:243], v[98:101]
	v_mfma_f32_16x16x32_bf16 v[26:29], v[150:153], v[240:243], v[26:29]
	v_mfma_f32_16x16x32_bf16 v[82:85], v[154:157], v[194:197], v[82:85]
	v_mfma_f32_16x16x32_bf16 v[10:13], v[162:165], v[194:197], v[10:13]
	v_mfma_f32_16x16x32_bf16 v[66:69], v[154:157], v[202:205], v[66:69]
	v_mfma_f32_16x16x32_bf16 v[2:5], v[162:165], v[202:205], v[2:5]
	v_mfma_f32_16x16x32_bf16 v[94:97], v[154:157], v[228:231], v[94:97]
	v_mfma_f32_16x16x32_bf16 v[22:25], v[162:165], v[228:231], v[22:25]
	v_mfma_f32_16x16x32_bf16 v[90:93], v[154:157], v[236:239], v[90:93]
	v_mfma_f32_16x16x32_bf16 v[18:21], v[162:165], v[236:239], v[18:21]
	v_mfma_f32_16x16x32_bf16 v[82:85], v[158:161], v[198:201], v[82:85]
	v_mfma_f32_16x16x32_bf16 v[10:13], v[166:169], v[198:201], v[10:13]
	v_mfma_f32_16x16x32_bf16 v[66:69], v[158:161], v[214:217], v[66:69]
	v_mfma_f32_16x16x32_bf16 v[2:5], v[166:169], v[214:217], v[2:5]
	v_mfma_f32_16x16x32_bf16 v[94:97], v[158:161], v[232:235], v[94:97]
	v_mfma_f32_16x16x32_bf16 v[22:25], v[166:169], v[232:235], v[22:25]
	v_mfma_f32_16x16x32_bf16 v[90:93], v[158:161], v[240:243], v[90:93]
	v_mfma_f32_16x16x32_bf16 v[18:21], v[166:169], v[240:243], v[18:21]
	s_barrier
	s_add_u32 s35, s35, 0x100
	s_addc_u32 s51, s51, 0
	s_cmp_ge_i32 s52, s67
	s_mov_b64 s[48:49], s[14:15]
	s_mov_b32 s46, s52
	s_cbranch_scc0 .LBB0_809
	s_movk_i32 s75, 0x2000
	s_movk_i32 s76, 0x3000
	s_and_b64 vcc, exec, s[30:31]
	s_cbranch_vccz .LBB0_784

; #define PG8_STAGE(bufoff, gbase, voff) do { _Pragma("unroll") for (int _i = 0; _i < 2; ++_i) \
;         __builtin_amdgcn_global_load_lds((const unsigned*)((const char*)(gbase) + (voff)[_i]), (PG8_LAS unsigned*)(lds + (bufoff) + ldsw + _i * 8192), 16, 0, 0); } while (0)
; #define PG8_LDA(dst, b, h) do { _Pragma("unroll") for (int m = 0; m < 4; ++m) _Pragma("unroll") for (int k = 0; k < 2; ++k) dst[m][k] = *(const PG8_LAS bf16x8*)(lds + PG8_SA(b, h) + aoff + m * 2048 + k * 1024); } while (0)
; #define PG8_LDB(dst, b, h) do { _Pragma("unroll") for (int n = 0; n < 2; ++n) _Pragma("unroll") for (int k = 0; k < 2; ++k) dst[n][k] = *(const PG8_LAS bf16x8*)(lds + PG8_SB(b, h) + boff + n * 2048 + k * 1024); } while (0)
; #define PG8_MMA(ai, bj, At, Bt) do { __builtin_amdgcn_s_setprio(1); _Pragma("unroll") for (int m = 0; m < 4; ++m) _Pragma("unroll") for (int n = 0; n < 2; ++n) _Pragma("unroll") for (int k = 0; k < 2; ++k) \
;         acc[ai][bj][m][n] = __builtin_amdgcn_mfma_f32_16x16x32_bf16(Bt[n][k], At[m][k], acc[ai][bj][m][n], 0, 0, 0); __builtin_amdgcn_s_setprio(0); } while (0)
; #define PG8_WAIT_V(n) asm volatile("s_waitcnt vmcnt(" #n ")" ::: "memory")
; #define PG8_WAIT_L(n) asm volatile("s_waitcnt lgkmcnt(" #n ")" ::: "memory")
; template <class Epi, class Sched, bool ALIGN_EPI = false, bool SP2 = false>
; __device__ __forceinline__ void gemm_phase(PG8_LAS unsigned char* lds, const Gemm g, const Sched& S, const Epi& E, const int wv) {
;     ...
;             const bool last = (t == nt - 2);
;             const char* a1 = cA + (size_t)(t + 1) * kstep;
;             const char* a2 = last ? nA : cA + (size_t)(t + 2) * kstep; const char* b2 = last ? nB : cB + (size_t)(t + 2) * kstep;
;             const char* a3 = a2 + kstep; const char* b3 = b2 + kstep;
;             if (last && has_next) S.a_ready(nxt);
;             if constexpr (SP2) {
;             PG8_LDB(B0, 0, 0); PG8_LDB(B1, 0, 1); PG8_SCHED; PG8_LDA(At, 0, 0); PG8_STAGE(PG8_SA(1, 1), a1 + hstepA, voffA);
;             PG8_WAIT_V(8); PG8_WAIT_L(0); PG8_BAR; PG8_MMA(0, 0, At, B0); PG8_MMA(0, 1, At, B1); PG8_BAR; PG8_SCHED;
;             PG8_LDA(At, 0, 1); PG8_STAGE(PG8_SB(0, 0), b2, voffB); PG8_STAGE(PG8_SB(0, 1), b2 + hstepB, voffB); PG8_STAGE(PG8_SA(0, 0), a2, voffA);
;             PG8_WAIT_V(8); PG8_WAIT_L(0); PG8_BAR; PG8_MMA(1, 0, At, B0); PG8_MMA(1, 1, At, B1); PG8_BAR; PG8_SCHED;
.LBB0_990:
	s_add_i32 s67, s44, 2
	s_add_u32 s34, s30, 0x100
	s_addc_u32 s35, s31, 0
	s_cmp_eq_u32 s59, s44
	s_cselect_b32 s45, s13, s35
	s_cselect_b32 s44, s12, s34
	s_cselect_b32 s69, s15, s66
	s_cselect_b32 s68, s14, s65
	ds_read_b128 v[114:117], v197
	ds_read_b128 v[126:129], v197 offset:1024
	ds_read_b128 v[138:141], v197 offset:2048
	ds_read_b128 v[142:145], v197 offset:3072
	ds_read_b128 v[146:149], v201
	ds_read_b128 v[150:153], v201 offset:1024
	ds_read_b128 v[154:157], v201 offset:2048
	ds_read_b128 v[158:161], v201 offset:3072
	s_add_i32 m0, s52, 0xc000
	ds_read_b128 v[162:165], v235
	ds_read_b128 v[166:169], v235 offset:1024
	ds_read_b128 v[170:173], v235 offset:2048
	ds_read_b128 v[174:177], v235 offset:3072
	ds_read_b128 v[178:181], v235 offset:4096
	ds_read_b128 v[182:185], v235 offset:5120
	ds_read_b128 v[204:207], v235 offset:6144
	ds_read_b128 v[208:211], v235 offset:7168
	global_load_lds_dwordx4 v200, s[30:31]
	s_add_i32 m0, s52, 0xe000
	s_nop 0
	global_load_lds_dwordx4 v202, s[30:31]
	s_waitcnt vmcnt(8) lgkmcnt(0)
	s_barrier
	v_mfma_f32_16x16x32_bf16 v[134:137], v[114:117], v[162:165], v[134:137]
	v_mfma_f32_16x16x32_bf16 v[130:133], v[138:141], v[162:165], v[130:133]
	v_mfma_f32_16x16x32_bf16 v[110:113], v[114:117], v[170:173], v[110:113]
	v_mfma_f32_16x16x32_bf16 v[106:109], v[138:141], v[170:173], v[106:109]
	v_mfma_f32_16x16x32_bf16 v[94:97], v[114:117], v[178:181], v[94:97]
	v_mfma_f32_16x16x32_bf16 v[90:93], v[138:141], v[178:181], v[90:93]
	v_mfma_f32_16x16x32_bf16 v[78:81], v[114:117], v[204:207], v[78:81]
	v_mfma_f32_16x16x32_bf16 v[74:77], v[138:141], v[204:207], v[74:77]
	v_mfma_f32_16x16x32_bf16 v[134:137], v[126:129], v[166:169], v[134:137]
	v_mfma_f32_16x16x32_bf16 v[130:133], v[142:145], v[166:169], v[130:133]
	v_mfma_f32_16x16x32_bf16 v[110:113], v[126:129], v[174:177], v[110:113]
	v_mfma_f32_16x16x32_bf16 v[106:109], v[142:145], v[174:177], v[106:109]
	v_mfma_f32_16x16x32_bf16 v[94:97], v[126:129], v[182:185], v[94:97]
	v_mfma_f32_16x16x32_bf16 v[90:93], v[142:145], v[182:185], v[90:93]
	v_mfma_f32_16x16x32_bf16 v[78:81], v[126:129], v[208:211], v[78:81]
	v_mfma_f32_16x16x32_bf16 v[74:77], v[142:145], v[208:211], v[74:77]
	v_mfma_f32_16x16x32_bf16 v[122:125], v[146:149], v[162:165], v[122:125]
	v_mfma_f32_16x16x32_bf16 v[118:121], v[154:157], v[162:165], v[118:121]
	v_mfma_f32_16x16x32_bf16 v[102:105], v[146:149], v[170:173], v[102:105]
	v_mfma_f32_16x16x32_bf16 v[98:101], v[154:157], v[170:173], v[98:101]
	v_mfma_f32_16x16x32_bf16 v[86:89], v[146:149], v[178:181], v[86:89]
	v_mfma_f32_16x16x32_bf16 v[82:85], v[154:157], v[178:181], v[82:85]
	v_mfma_f32_16x16x32_bf16 v[70:73], v[146:149], v[204:207], v[70:73]
	v_mfma_f32_16x16x32_bf16 v[66:69], v[154:157], v[204:207], v[66:69]
	v_mfma_f32_16x16x32_bf16 v[122:125], v[150:153], v[166:169], v[122:125]
	v_mfma_f32_16x16x32_bf16 v[118:121], v[158:161], v[166:169], v[118:121]
	v_mfma_f32_16x16x32_bf16 v[102:105], v[150:153], v[174:177], v[102:105]
	v_mfma_f32_16x16x32_bf16 v[98:101], v[158:161], v[174:177], v[98:101]
	v_mfma_f32_16x16x32_bf16 v[86:89], v[150:153], v[182:185], v[86:89]
	v_mfma_f32_16x16x32_bf16 v[82:85], v[158:161], v[182:185], v[82:85]
	v_mfma_f32_16x16x32_bf16 v[70:73], v[150:153], v[208:211], v[70:73]
	v_mfma_f32_16x16x32_bf16 v[66:69], v[158:161], v[208:211], v[66:69]
	s_barrier
	v_lshl_add_u64 v[190:191], s[68:69], 0, v[0:1]
	s_add_i32 m0, s47, 0x10000
	ds_read_b128 v[162:165], v235 offset:16384
	ds_read_b128 v[166:169], v235 offset:17408
	ds_read_b128 v[170:173], v235 offset:18432
	ds_read_b128 v[174:177], v235 offset:19456
	ds_read_b128 v[178:181], v235 offset:20480
	ds_read_b128 v[182:185], v235 offset:21504
	ds_read_b128 v[204:207], v235 offset:22528
	ds_read_b128 v[208:211], v235 offset:23552
	global_load_lds_dwordx4 v[190:191], off
	s_add_i32 m0, s47, 0x12000
	s_add_u32 s30, s68, s2
	v_lshl_add_u64 v[192:193], s[68:69], 0, v[198:199]
	s_addc_u32 s31, s69, s3
	s_add_i32 s68, s47, 0x14000
	global_load_lds_dwordx4 v[192:193], off
	v_lshl_add_u64 v[212:213], s[30:31], 0, v[0:1]
	s_mov_b32 m0, s68
	v_lshl_add_u64 v[214:215], s[30:31], 0, v[198:199]
	global_load_lds_dwordx4 v[212:213], off
	s_add_i32 m0, s68, 0x2000
	global_load_lds_dwordx4 v[214:215], off
	s_mov_b32 m0, s52
	global_load_lds_dwordx4 v194, s[44:45]
	s_mov_b32 m0, s53
	s_nop 0
	global_load_lds_dwordx4 v196, s[44:45]
	s_waitcnt vmcnt(8) lgkmcnt(0)
	s_barrier
	v_mfma_f32_16x16x32_bf16 v[62:65], v[114:117], v[162:165], v[62:65]
	v_mfma_f32_16x16x32_bf16 v[58:61], v[138:141], v[162:165], v[58:61]
	v_mfma_f32_16x16x32_bf16 v[46:49], v[114:117], v[170:173], v[46:49]
	v_mfma_f32_16x16x32_bf16 v[42:45], v[138:141], v[170:173], v[42:45]
	v_mfma_f32_16x16x32_bf16 v[30:33], v[114:117], v[178:181], v[30:33]
	v_mfma_f32_16x16x32_bf16 v[26:29], v[138:141], v[178:181], v[26:29]
	v_mfma_f32_16x16x32_bf16 v[14:17], v[114:117], v[204:207], v[14:17]
	v_mfma_f32_16x16x32_bf16 v[10:13], v[138:141], v[204:207], v[10:13]
	v_mfma_f32_16x16x32_bf16 v[62:65], v[126:129], v[166:169], v[62:65]
	v_mfma_f32_16x16x32_bf16 v[58:61], v[142:145], v[166:169], v[58:61]
	v_mfma_f32_16x16x32_bf16 v[46:49], v[126:129], v[174:177], v[46:49]
	v_mfma_f32_16x16x32_bf16 v[42:45], v[142:145], v[174:177], v[42:45]
	v_mfma_f32_16x16x32_bf16 v[30:33], v[126:129], v[182:185], v[30:33]
	v_mfma_f32_16x16x32_bf16 v[26:29], v[142:145], v[182:185], v[26:29]
	v_mfma_f32_16x16x32_bf16 v[14:17], v[126:129], v[208:211], v[14:17]
	v_mfma_f32_16x16x32_bf16 v[10:13], v[142:145], v[208:211], v[10:13]
	v_mfma_f32_16x16x32_bf16 v[54:57], v[146:149], v[162:165], v[54:57]
	v_mfma_f32_16x16x32_bf16 v[50:53], v[154:157], v[162:165], v[50:53]
	v_mfma_f32_16x16x32_bf16 v[38:41], v[146:149], v[170:173], v[38:41]
	v_mfma_f32_16x16x32_bf16 v[34:37], v[154:157], v[170:173], v[34:37]
	v_mfma_f32_16x16x32_bf16 v[22:25], v[146:149], v[178:181], v[22:25]
	v_mfma_f32_16x16x32_bf16 v[18:21], v[154:157], v[178:181], v[18:21]
	v_mfma_f32_16x16x32_bf16 v[6:9], v[146:149], v[204:207], v[6:9]
	v_mfma_f32_16x16x32_bf16 v[2:5], v[154:157], v[204:207], v[2:5]
	v_mfma_f32_16x16x32_bf16 v[54:57], v[150:153], v[166:169], v[54:57]
	v_mfma_f32_16x16x32_bf16 v[50:53], v[158:161], v[166:169], v[50:53]
	v_mfma_f32_16x16x32_bf16 v[38:41], v[150:153], v[174:177], v[38:41]
	v_mfma_f32_16x16x32_bf16 v[34:37], v[158:161], v[174:177], v[34:37]
	v_mfma_f32_16x16x32_bf16 v[22:25], v[150:153], v[182:185], v[22:25]
	v_mfma_f32_16x16x32_bf16 v[18:21], v[158:161], v[182:185], v[18:21]
	v_mfma_f32_16x16x32_bf16 v[6:9], v[150:153], v[208:211], v[6:9]
	v_mfma_f32_16x16x32_bf16 v[2:5], v[158:161], v[208:211], v[2:5]
	s_barrier
; #define PG8_STAGE(bufoff, gbase, voff) do { _Pragma("unroll") for (int _i = 0; _i < 2; ++_i) \
;         __builtin_amdgcn_global_load_lds((const unsigned*)((const char*)(gbase) + (voff)[_i]), (PG8_LAS unsigned*)(lds + (bufoff) + ldsw + _i * 8192), 16, 0, 0); } while (0)
; #define PG8_LDA(dst, b, h) do { _Pragma("unroll") for (int m = 0; m < 4; ++m) _Pragma("unroll") for (int k = 0; k < 2; ++k) dst[m][k] = *(const PG8_LAS bf16x8*)(lds + PG8_SA(b, h) + aoff + m * 2048 + k * 1024); } while (0)
; #define PG8_LDB(dst, b, h) do { _Pragma("unroll") for (int n = 0; n < 2; ++n) _Pragma("unroll") for (int k = 0; k < 2; ++k) dst[n][k] = *(const PG8_LAS bf16x8*)(lds + PG8_SB(b, h) + boff + n * 2048 + k * 1024); } while (0)
; #define PG8_MMA(ai, bj, At, Bt) do { __builtin_amdgcn_s_setprio(1); _Pragma("unroll") for (int m = 0; m < 4; ++m) _Pragma("unroll") for (int n = 0; n < 2; ++n) _Pragma("unroll") for (int k = 0; k < 2; ++k) \
;         acc[ai][bj][m][n] = __builtin_amdgcn_mfma_f32_16x16x32_bf16(Bt[n][k], At[m][k], acc[ai][bj][m][n], 0, 0, 0); __builtin_amdgcn_s_setprio(0); } while (0)
; #define PG8_WAIT_V(n) asm volatile("s_waitcnt vmcnt(" #n ")" ::: "memory")
; #define PG8_WAIT_L(n) asm volatile("s_waitcnt lgkmcnt(" #n ")" ::: "memory")
; #define PG8_BAR __builtin_amdgcn_s_barrier()
; #define PG8_SCHED __builtin_amdgcn_sched_barrier(0)
; template <class Epi, class Sched, bool ALIGN_EPI = false, bool SP2 = false>
; __device__ __forceinline__ void gemm_phase(PG8_LAS unsigned char* lds, const Gemm g, const Sched& S, const Epi& E, const int wv) {
;     ...
;             PG8_LDB(B0, 1, 0); PG8_LDB(B1, 1, 1); PG8_SCHED; PG8_LDA(At, 1, 0); PG8_STAGE(PG8_SA(0, 1), a2 + hstepA, voffA);
;             PG8_WAIT_V(8); PG8_WAIT_L(0); PG8_BAR; PG8_MMA(0, 0, At, B0); PG8_MMA(0, 1, At, B1); PG8_BAR; PG8_SCHED;
;             PG8_LDA(At, 1, 1); PG8_STAGE(PG8_SB(1, 0), b3, voffB); PG8_STAGE(PG8_SB(1, 1), b3 + hstepB, voffB); PG8_STAGE(PG8_SA(1, 0), a3, voffA);
;             PG8_WAIT_V(8); PG8_WAIT_L(0); PG8_BAR; PG8_MMA(1, 0, At, B0); PG8_MMA(1, 1, At, B1); PG8_BAR; PG8_SCHED;
	ds_read_b128 v[114:117], v203
	ds_read_b128 v[126:129], v203 offset:1024
	ds_read_b128 v[138:141], v203 offset:2048
	ds_read_b128 v[142:145], v203 offset:3072
	ds_read_b128 v[146:149], v216
	ds_read_b128 v[150:153], v216 offset:1024
	ds_read_b128 v[154:157], v216 offset:2048
	ds_read_b128 v[158:161], v216 offset:3072
	s_add_u32 s30, s44, 0x180000
	s_addc_u32 s31, s45, 0
	s_mov_b32 m0, s54
	ds_read_b128 v[162:165], v235 offset:32768
	ds_read_b128 v[166:169], v235 offset:33792
	ds_read_b128 v[170:173], v235 offset:34816
	ds_read_b128 v[174:177], v235 offset:35840
	ds_read_b128 v[178:181], v235 offset:36864
	ds_read_b128 v[182:185], v235 offset:37888
	ds_read_b128 v[204:207], v235 offset:38912
	ds_read_b128 v[208:211], v235 offset:39936
	global_load_lds_dwordx4 v194, s[30:31]
	s_mov_b32 m0, s55
	s_nop 0
	global_load_lds_dwordx4 v196, s[30:31]
	s_waitcnt vmcnt(8) lgkmcnt(0)
	s_barrier
	v_mfma_f32_16x16x32_bf16 v[134:137], v[114:117], v[162:165], v[134:137]
	v_mfma_f32_16x16x32_bf16 v[130:133], v[138:141], v[162:165], v[130:133]
	v_mfma_f32_16x16x32_bf16 v[110:113], v[114:117], v[170:173], v[110:113]
	v_mfma_f32_16x16x32_bf16 v[106:109], v[138:141], v[170:173], v[106:109]
	v_mfma_f32_16x16x32_bf16 v[94:97], v[114:117], v[178:181], v[94:97]
	v_mfma_f32_16x16x32_bf16 v[90:93], v[138:141], v[178:181], v[90:93]
	v_mfma_f32_16x16x32_bf16 v[78:81], v[114:117], v[204:207], v[78:81]
	v_mfma_f32_16x16x32_bf16 v[74:77], v[138:141], v[204:207], v[74:77]
	v_mfma_f32_16x16x32_bf16 v[134:137], v[126:129], v[166:169], v[134:137]
	v_mfma_f32_16x16x32_bf16 v[130:133], v[142:145], v[166:169], v[130:133]
	v_mfma_f32_16x16x32_bf16 v[110:113], v[126:129], v[174:177], v[110:113]
	v_mfma_f32_16x16x32_bf16 v[106:109], v[142:145], v[174:177], v[106:109]
	v_mfma_f32_16x16x32_bf16 v[94:97], v[126:129], v[182:185], v[94:97]
	v_mfma_f32_16x16x32_bf16 v[90:93], v[142:145], v[182:185], v[90:93]
	v_mfma_f32_16x16x32_bf16 v[78:81], v[126:129], v[208:211], v[78:81]
	v_mfma_f32_16x16x32_bf16 v[74:77], v[142:145], v[208:211], v[74:77]
	v_mfma_f32_16x16x32_bf16 v[122:125], v[146:149], v[162:165], v[122:125]
	v_mfma_f32_16x16x32_bf16 v[118:121], v[154:157], v[162:165], v[118:121]
	v_mfma_f32_16x16x32_bf16 v[102:105], v[146:149], v[170:173], v[102:105]
	v_mfma_f32_16x16x32_bf16 v[98:101], v[154:157], v[170:173], v[98:101]
	v_mfma_f32_16x16x32_bf16 v[86:89], v[146:149], v[178:181], v[86:89]
	v_mfma_f32_16x16x32_bf16 v[82:85], v[154:157], v[178:181], v[82:85]
	v_mfma_f32_16x16x32_bf16 v[70:73], v[146:149], v[204:207], v[70:73]
	v_mfma_f32_16x16x32_bf16 v[66:69], v[154:157], v[204:207], v[66:69]
	v_mfma_f32_16x16x32_bf16 v[122:125], v[150:153], v[166:169], v[122:125]
	v_mfma_f32_16x16x32_bf16 v[118:121], v[158:161], v[166:169], v[118:121]
	v_mfma_f32_16x16x32_bf16 v[102:105], v[150:153], v[174:177], v[102:105]
	v_mfma_f32_16x16x32_bf16 v[98:101], v[158:161], v[174:177], v[98:101]
	v_mfma_f32_16x16x32_bf16 v[86:89], v[150:153], v[182:185], v[86:89]
	v_mfma_f32_16x16x32_bf16 v[82:85], v[158:161], v[182:185], v[82:85]
	v_mfma_f32_16x16x32_bf16 v[70:73], v[150:153], v[208:211], v[70:73]
	v_mfma_f32_16x16x32_bf16 v[66:69], v[158:161], v[208:211], v[66:69]
	s_barrier
	s_add_i32 m0, s47, 0x17f80
	ds_read_b128 v[162:165], v235 offset:49152
	ds_read_b128 v[166:169], v235 offset:50176
	ds_read_b128 v[170:173], v235 offset:51200
	ds_read_b128 v[174:177], v235 offset:52224
	ds_read_b128 v[178:181], v235 offset:53248
	ds_read_b128 v[182:185], v235 offset:54272
	ds_read_b128 v[204:207], v235 offset:55296
	ds_read_b128 v[208:211], v235 offset:56320
	global_load_lds_dwordx4 v[190:191], off offset:128
	s_add_i32 m0, s47, 0x19f80
	global_load_lds_dwordx4 v[192:193], off offset:128
	s_add_i32 m0, s47, 0x1bf80
	s_nop 0
	global_load_lds_dwordx4 v[212:213], off offset:128
	s_add_i32 m0, s47, 0x1df80
	s_nop 0
	global_load_lds_dwordx4 v[214:215], off offset:128
	s_add_i32 m0, s57, 0xffffff80
	s_nop 0
	global_load_lds_dwordx4 v194, s[44:45] offset:128
	s_add_i32 m0, s58, 0xffffff80
	s_nop 0
	global_load_lds_dwordx4 v196, s[44:45] offset:128
	s_waitcnt vmcnt(8) lgkmcnt(0)
	s_barrier
	v_mfma_f32_16x16x32_bf16 v[62:65], v[114:117], v[162:165], v[62:65]
	v_mfma_f32_16x16x32_bf16 v[58:61], v[138:141], v[162:165], v[58:61]
	v_mfma_f32_16x16x32_bf16 v[46:49], v[114:117], v[170:173], v[46:49]
	v_mfma_f32_16x16x32_bf16 v[42:45], v[138:141], v[170:173], v[42:45]
	v_mfma_f32_16x16x32_bf16 v[30:33], v[114:117], v[178:181], v[30:33]
	v_mfma_f32_16x16x32_bf16 v[26:29], v[138:141], v[178:181], v[26:29]
	v_mfma_f32_16x16x32_bf16 v[14:17], v[114:117], v[204:207], v[14:17]
	v_mfma_f32_16x16x32_bf16 v[10:13], v[138:141], v[204:207], v[10:13]
	v_mfma_f32_16x16x32_bf16 v[62:65], v[126:129], v[166:169], v[62:65]
	v_mfma_f32_16x16x32_bf16 v[58:61], v[142:145], v[166:169], v[58:61]
	v_mfma_f32_16x16x32_bf16 v[46:49], v[126:129], v[174:177], v[46:49]
	v_mfma_f32_16x16x32_bf16 v[42:45], v[142:145], v[174:177], v[42:45]
	v_mfma_f32_16x16x32_bf16 v[30:33], v[126:129], v[182:185], v[30:33]
	v_mfma_f32_16x16x32_bf16 v[26:29], v[142:145], v[182:185], v[26:29]
	v_mfma_f32_16x16x32_bf16 v[14:17], v[126:129], v[208:211], v[14:17]
	v_mfma_f32_16x16x32_bf16 v[10:13], v[142:145], v[208:211], v[10:13]
	v_mfma_f32_16x16x32_bf16 v[54:57], v[146:149], v[162:165], v[54:57]
	v_mfma_f32_16x16x32_bf16 v[50:53], v[154:157], v[162:165], v[50:53]
	v_mfma_f32_16x16x32_bf16 v[38:41], v[146:149], v[170:173], v[38:41]
	v_mfma_f32_16x16x32_bf16 v[34:37], v[154:157], v[170:173], v[34:37]
	v_mfma_f32_16x16x32_bf16 v[22:25], v[146:149], v[178:181], v[22:25]
	v_mfma_f32_16x16x32_bf16 v[18:21], v[154:157], v[178:181], v[18:21]
	v_mfma_f32_16x16x32_bf16 v[6:9], v[146:149], v[204:207], v[6:9]
	v_mfma_f32_16x16x32_bf16 v[2:5], v[154:157], v[204:207], v[2:5]
	v_mfma_f32_16x16x32_bf16 v[54:57], v[150:153], v[166:169], v[54:57]
	v_mfma_f32_16x16x32_bf16 v[50:53], v[158:161], v[166:169], v[50:53]
	v_mfma_f32_16x16x32_bf16 v[38:41], v[150:153], v[174:177], v[38:41]
	v_mfma_f32_16x16x32_bf16 v[34:37], v[158:161], v[174:177], v[34:37]
	v_mfma_f32_16x16x32_bf16 v[22:25], v[150:153], v[182:185], v[22:25]
	v_mfma_f32_16x16x32_bf16 v[18:21], v[158:161], v[182:185], v[18:21]
	v_mfma_f32_16x16x32_bf16 v[6:9], v[150:153], v[208:211], v[6:9]
	v_mfma_f32_16x16x32_bf16 v[2:5], v[158:161], v[208:211], v[2:5]
	s_barrier
	s_add_u32 s65, s65, 0x100
	s_addc_u32 s66, s66, 0
	s_cmp_ge_i32 s67, s56
	s_mov_b64 s[30:31], s[34:35]
	s_mov_b32 s44, s67
	s_cbranch_scc0 .LBB0_990
	s_movk_i32 s68, 0x4000
	s_movk_i32 s69, 0x6000
	s_mov_b32 s70, 0x18000
	s_mov_b32 s71, 0x3f317217
	v_readlane_b32 s67, v255, 30
	s_and_b64 vcc, exec, s[28:29]
	s_cbranch_vccz .LBB0_966

; #define PG8_STAGE(bufoff, gbase, voff) do { _Pragma("unroll") for (int _i = 0; _i < 2; ++_i) \
;         __builtin_amdgcn_global_load_lds((const unsigned*)((const char*)(gbase) + (voff)[_i]), (PG8_LAS unsigned*)(lds + (bufoff) + ldsw + _i * 8192), 16, 0, 0); } while (0)
; #define PG8_LDA(dst, b, h) do { _Pragma("unroll") for (int m = 0; m < 4; ++m) _Pragma("unroll") for (int k = 0; k < 2; ++k) dst[m][k] = *(const PG8_LAS bf16x8*)(lds + PG8_SA(b, h) + aoff + m * 2048 + k * 1024); } while (0)
; #define PG8_LDB(dst, b, h) do { _Pragma("unroll") for (int n = 0; n < 2; ++n) _Pragma("unroll") for (int k = 0; k < 2; ++k) dst[n][k] = *(const PG8_LAS bf16x8*)(lds + PG8_SB(b, h) + boff + n * 2048 + k * 1024); } while (0)
; #define PG8_MMA(ai, bj, At, Bt) do { __builtin_amdgcn_s_setprio(1); _Pragma("unroll") for (int m = 0; m < 4; ++m) _Pragma("unroll") for (int n = 0; n < 2; ++n) _Pragma("unroll") for (int k = 0; k < 2; ++k) \
;         acc[ai][bj][m][n] = __builtin_amdgcn_mfma_f32_16x16x32_bf16(Bt[n][k], At[m][k], acc[ai][bj][m][n], 0, 0, 0); __builtin_amdgcn_s_setprio(0); } while (0)
; #define PG8_WAIT_V(n) asm volatile("s_waitcnt vmcnt(" #n ")" ::: "memory")
; #define PG8_WAIT_L(n) asm volatile("s_waitcnt lgkmcnt(" #n ")" ::: "memory")
; template <class Epi, class Sched, bool ALIGN_EPI = false, bool SP2 = false>
; __device__ __forceinline__ void gemm_phase(PG8_LAS unsigned char* lds, const Gemm g, const Sched& S, const Epi& E, const int wv) {
;     ...
;             const bool last = (t == nt - 2);
;             const char* a1 = cA + (size_t)(t + 1) * kstep;
;             const char* a2 = last ? nA : cA + (size_t)(t + 2) * kstep; const char* b2 = last ? nB : cB + (size_t)(t + 2) * kstep;
;             const char* a3 = a2 + kstep; const char* b3 = b2 + kstep;
;             if (last && has_next) S.a_ready(nxt);
;             if constexpr (SP2) {
;             PG8_LDB(B0, 0, 0); PG8_LDB(B1, 0, 1); PG8_SCHED; PG8_LDA(At, 0, 0); PG8_STAGE(PG8_SA(1, 1), a1 + hstepA, voffA);
;             PG8_WAIT_V(8); PG8_WAIT_L(0); PG8_BAR; PG8_MMA(0, 0, At, B0); PG8_MMA(0, 1, At, B1); PG8_BAR; PG8_SCHED;
;             PG8_LDA(At, 0, 1); PG8_STAGE(PG8_SB(0, 0), b2, voffB); PG8_STAGE(PG8_SB(0, 1), b2 + hstepB, voffB); PG8_STAGE(PG8_SA(0, 0), a2, voffA);
;             PG8_WAIT_V(8); PG8_WAIT_L(0); PG8_BAR; PG8_MMA(1, 0, At, B0); PG8_MMA(1, 1, At, B1); PG8_BAR; PG8_SCHED;
.LBB0_1074:
	s_add_i32 s63, s30, 2
	s_add_u32 s64, s28, 0xfff80080
	s_addc_u32 s31, s29, -1
	s_cmp_eq_u32 s57, s30
	s_cselect_b32 s31, s17, s31
	s_cselect_b32 s30, s40, s64
	s_cselect_b32 s65, s19, s62
	s_cselect_b32 s64, s18, s41
	ds_read_b128 v[164:167], v147
	ds_read_b128 v[168:171], v147 offset:1024
	ds_read_b128 v[172:175], v147 offset:2048
	ds_read_b128 v[176:179], v147 offset:3072
	ds_read_b128 v[180:183], v149
	ds_read_b128 v[194:197], v149 offset:1024
	ds_read_b128 v[198:201], v149 offset:2048
	ds_read_b128 v[202:205], v149 offset:3072
	s_add_i32 m0, s47, 0xc000
	ds_read_b128 v[206:209], v163
	ds_read_b128 v[210:213], v163 offset:1024
	ds_read_b128 v[214:217], v163 offset:2048
	ds_read_b128 v[228:231], v163 offset:3072
	ds_read_b128 v[232:235], v163 offset:4096
	ds_read_b128 v[236:239], v163 offset:5120
	ds_read_b128 v[240:243], v163 offset:6144
	ds_read_b128 v[244:247], v163 offset:7168
	global_load_lds_dwordx4 v146, s[28:29]
	s_add_i32 m0, s47, 0xe000
	s_nop 0
	global_load_lds_dwordx4 v148, s[28:29]
	s_waitcnt vmcnt(8) lgkmcnt(0)
	s_barrier
	v_mfma_f32_16x16x32_bf16 v[130:133], v[164:167], v[206:209], v[130:133]
	v_mfma_f32_16x16x32_bf16 v[126:129], v[172:175], v[206:209], v[126:129]
	v_mfma_f32_16x16x32_bf16 v[114:117], v[164:167], v[214:217], v[114:117]
	v_mfma_f32_16x16x32_bf16 v[110:113], v[172:175], v[214:217], v[110:113]
	v_mfma_f32_16x16x32_bf16 v[98:101], v[164:167], v[232:235], v[98:101]
	v_mfma_f32_16x16x32_bf16 v[94:97], v[172:175], v[232:235], v[94:97]
	v_mfma_f32_16x16x32_bf16 v[82:85], v[164:167], v[240:243], v[82:85]
	v_mfma_f32_16x16x32_bf16 v[78:81], v[172:175], v[240:243], v[78:81]
	v_mfma_f32_16x16x32_bf16 v[130:133], v[168:171], v[210:213], v[130:133]
	v_mfma_f32_16x16x32_bf16 v[126:129], v[176:179], v[210:213], v[126:129]
	v_mfma_f32_16x16x32_bf16 v[114:117], v[168:171], v[228:231], v[114:117]
	v_mfma_f32_16x16x32_bf16 v[110:113], v[176:179], v[228:231], v[110:113]
	v_mfma_f32_16x16x32_bf16 v[98:101], v[168:171], v[236:239], v[98:101]
	v_mfma_f32_16x16x32_bf16 v[94:97], v[176:179], v[236:239], v[94:97]
	v_mfma_f32_16x16x32_bf16 v[82:85], v[168:171], v[244:247], v[82:85]
	v_mfma_f32_16x16x32_bf16 v[78:81], v[176:179], v[244:247], v[78:81]
	v_mfma_f32_16x16x32_bf16 v[122:125], v[180:183], v[206:209], v[122:125]
	v_mfma_f32_16x16x32_bf16 v[118:121], v[198:201], v[206:209], v[118:121]
	v_mfma_f32_16x16x32_bf16 v[106:109], v[180:183], v[214:217], v[106:109]
	v_mfma_f32_16x16x32_bf16 v[102:105], v[198:201], v[214:217], v[102:105]
	v_mfma_f32_16x16x32_bf16 v[90:93], v[180:183], v[232:235], v[90:93]
	v_mfma_f32_16x16x32_bf16 v[86:89], v[198:201], v[232:235], v[86:89]
	v_mfma_f32_16x16x32_bf16 v[74:77], v[180:183], v[240:243], v[74:77]
	v_mfma_f32_16x16x32_bf16 v[70:73], v[198:201], v[240:243], v[70:73]
	v_mfma_f32_16x16x32_bf16 v[122:125], v[194:197], v[210:213], v[122:125]
	v_mfma_f32_16x16x32_bf16 v[118:121], v[202:205], v[210:213], v[118:121]
	v_mfma_f32_16x16x32_bf16 v[106:109], v[194:197], v[228:231], v[106:109]
	v_mfma_f32_16x16x32_bf16 v[102:105], v[202:205], v[228:231], v[102:105]
	v_mfma_f32_16x16x32_bf16 v[90:93], v[194:197], v[236:239], v[90:93]
	v_mfma_f32_16x16x32_bf16 v[86:89], v[202:205], v[236:239], v[86:89]
	v_mfma_f32_16x16x32_bf16 v[74:77], v[194:197], v[244:247], v[74:77]
	v_mfma_f32_16x16x32_bf16 v[70:73], v[202:205], v[244:247], v[70:73]
	s_barrier
	v_lshl_add_u64 v[150:151], s[64:65], 0, v[138:139]
	s_add_i32 m0, s45, 0x10000
	ds_read_b128 v[206:209], v163 offset:16384
	ds_read_b128 v[210:213], v163 offset:17408
	ds_read_b128 v[214:217], v163 offset:18432
	ds_read_b128 v[228:231], v163 offset:19456
	ds_read_b128 v[232:235], v163 offset:20480
	ds_read_b128 v[236:239], v163 offset:21504
	ds_read_b128 v[240:243], v163 offset:22528
	ds_read_b128 v[244:247], v163 offset:23552
	global_load_lds_dwordx4 v[150:151], off
	s_add_i32 m0, s45, 0x12000
	v_lshl_add_u64 v[184:185], s[64:65], 0, v[134:135]
	s_add_u32 s64, s64, s0
	s_addc_u32 s65, s65, s1
	s_add_i32 s66, s45, 0x14000
	global_load_lds_dwordx4 v[184:185], off
	s_mov_b32 m0, s66
	global_load_lds_dwordx4 v138, s[64:65]
	s_add_i32 m0, s66, 0x2000
	global_load_lds_dwordx4 v134, s[64:65]
	s_mov_b32 m0, s47
	global_load_lds_dwordx4 v140, s[30:31]
	s_mov_b32 m0, s48
	s_nop 0
	global_load_lds_dwordx4 v136, s[30:31]
	s_waitcnt vmcnt(8) lgkmcnt(0)
	s_barrier
	v_mfma_f32_16x16x32_bf16 v[66:69], v[164:167], v[206:209], v[66:69]
	v_mfma_f32_16x16x32_bf16 v[62:65], v[172:175], v[206:209], v[62:65]
	v_mfma_f32_16x16x32_bf16 v[50:53], v[164:167], v[214:217], v[50:53]
	v_mfma_f32_16x16x32_bf16 v[46:49], v[172:175], v[214:217], v[46:49]
	v_mfma_f32_16x16x32_bf16 v[34:37], v[164:167], v[232:235], v[34:37]
	v_mfma_f32_16x16x32_bf16 v[30:33], v[172:175], v[232:235], v[30:33]
	v_mfma_f32_16x16x32_bf16 v[18:21], v[164:167], v[240:243], v[18:21]
	v_mfma_f32_16x16x32_bf16 v[14:17], v[172:175], v[240:243], v[14:17]
	v_mfma_f32_16x16x32_bf16 v[66:69], v[168:171], v[210:213], v[66:69]
	v_mfma_f32_16x16x32_bf16 v[62:65], v[176:179], v[210:213], v[62:65]
	v_mfma_f32_16x16x32_bf16 v[50:53], v[168:171], v[228:231], v[50:53]
	v_mfma_f32_16x16x32_bf16 v[46:49], v[176:179], v[228:231], v[46:49]
	v_mfma_f32_16x16x32_bf16 v[34:37], v[168:171], v[236:239], v[34:37]
	v_mfma_f32_16x16x32_bf16 v[30:33], v[176:179], v[236:239], v[30:33]
	v_mfma_f32_16x16x32_bf16 v[18:21], v[168:171], v[244:247], v[18:21]
	v_mfma_f32_16x16x32_bf16 v[14:17], v[176:179], v[244:247], v[14:17]
	v_mfma_f32_16x16x32_bf16 v[58:61], v[180:183], v[206:209], v[58:61]
	v_mfma_f32_16x16x32_bf16 v[54:57], v[198:201], v[206:209], v[54:57]
	v_mfma_f32_16x16x32_bf16 v[42:45], v[180:183], v[214:217], v[42:45]
	v_mfma_f32_16x16x32_bf16 v[38:41], v[198:201], v[214:217], v[38:41]
	v_mfma_f32_16x16x32_bf16 v[26:29], v[180:183], v[232:235], v[26:29]
	v_mfma_f32_16x16x32_bf16 v[22:25], v[198:201], v[232:235], v[22:25]
	v_mfma_f32_16x16x32_bf16 v[10:13], v[180:183], v[240:243], v[10:13]
	v_mfma_f32_16x16x32_bf16 v[6:9], v[198:201], v[240:243], v[6:9]
	v_mfma_f32_16x16x32_bf16 v[58:61], v[194:197], v[210:213], v[58:61]
	v_mfma_f32_16x16x32_bf16 v[54:57], v[202:205], v[210:213], v[54:57]
	v_mfma_f32_16x16x32_bf16 v[42:45], v[194:197], v[228:231], v[42:45]
	v_mfma_f32_16x16x32_bf16 v[38:41], v[202:205], v[228:231], v[38:41]
	v_mfma_f32_16x16x32_bf16 v[26:29], v[194:197], v[236:239], v[26:29]
	v_mfma_f32_16x16x32_bf16 v[22:25], v[202:205], v[236:239], v[22:25]
	v_mfma_f32_16x16x32_bf16 v[10:13], v[194:197], v[244:247], v[10:13]
	v_mfma_f32_16x16x32_bf16 v[6:9], v[202:205], v[244:247], v[6:9]
	s_barrier
; #define PG8_STAGE(bufoff, gbase, voff) do { _Pragma("unroll") for (int _i = 0; _i < 2; ++_i) \
;         __builtin_amdgcn_global_load_lds((const unsigned*)((const char*)(gbase) + (voff)[_i]), (PG8_LAS unsigned*)(lds + (bufoff) + ldsw + _i * 8192), 16, 0, 0); } while (0)
; #define PG8_LDA(dst, b, h) do { _Pragma("unroll") for (int m = 0; m < 4; ++m) _Pragma("unroll") for (int k = 0; k < 2; ++k) dst[m][k] = *(const PG8_LAS bf16x8*)(lds + PG8_SA(b, h) + aoff + m * 2048 + k * 1024); } while (0)
; #define PG8_LDB(dst, b, h) do { _Pragma("unroll") for (int n = 0; n < 2; ++n) _Pragma("unroll") for (int k = 0; k < 2; ++k) dst[n][k] = *(const PG8_LAS bf16x8*)(lds + PG8_SB(b, h) + boff + n * 2048 + k * 1024); } while (0)
; #define PG8_MMA(ai, bj, At, Bt) do { __builtin_amdgcn_s_setprio(1); _Pragma("unroll") for (int m = 0; m < 4; ++m) _Pragma("unroll") for (int n = 0; n < 2; ++n) _Pragma("unroll") for (int k = 0; k < 2; ++k) \
;         acc[ai][bj][m][n] = __builtin_amdgcn_mfma_f32_16x16x32_bf16(Bt[n][k], At[m][k], acc[ai][bj][m][n], 0, 0, 0); __builtin_amdgcn_s_setprio(0); } while (0)
; #define PG8_WAIT_V(n) asm volatile("s_waitcnt vmcnt(" #n ")" ::: "memory")
; #define PG8_WAIT_L(n) asm volatile("s_waitcnt lgkmcnt(" #n ")" ::: "memory")
; template <class Epi, class Sched, bool ALIGN_EPI = false, bool SP2 = false>
; __device__ __forceinline__ void gemm_phase(PG8_LAS unsigned char* lds, const Gemm g, const Sched& S, const Epi& E, const int wv) {
;     ...
;         for (int t = 0; t < nt; t += 2) {
;             const bool last = (t == nt - 2);
;             const char* a1 = cA + (size_t)(t + 1) * kstep;
;             const char* a2 = last ? nA : cA + (size_t)(t + 2) * kstep; const char* b2 = last ? nB : cB + (size_t)(t + 2) * kstep;
;             const char* a3 = a2 + kstep; const char* b3 = b2 + kstep;
;             if (last && has_next) S.a_ready(nxt);
;     ...
;             PG8_LDB(B0, 1, 0); PG8_LDB(B1, 1, 1); PG8_SCHED; PG8_LDA(At, 1, 0); PG8_STAGE(PG8_SA(0, 1), a2 + hstepA, voffA);
;             PG8_WAIT_V(8); PG8_WAIT_L(0); PG8_BAR; PG8_MMA(0, 0, At, B0); PG8_MMA(0, 1, At, B1); PG8_BAR; PG8_SCHED;
;             PG8_LDA(At, 1, 1); PG8_STAGE(PG8_SB(1, 0), b3, voffB); PG8_STAGE(PG8_SB(1, 1), b3 + hstepB, voffB); PG8_STAGE(PG8_SA(1, 0), a3, voffA);
;             PG8_WAIT_V(8); PG8_WAIT_L(0); PG8_BAR; PG8_MMA(1, 0, At, B0); PG8_MMA(1, 1, At, B1); PG8_BAR; PG8_SCHED;
	ds_read_b128 v[164:167], v152
	ds_read_b128 v[168:171], v152 offset:1024
	ds_read_b128 v[172:175], v152 offset:2048
	ds_read_b128 v[176:179], v152 offset:3072
	ds_read_b128 v[180:183], v154
	ds_read_b128 v[194:197], v154 offset:1024
	ds_read_b128 v[198:201], v154 offset:2048
	ds_read_b128 v[202:205], v154 offset:3072
	s_mov_b32 m0, s49
	ds_read_b128 v[206:209], v163 offset:32768
	ds_read_b128 v[210:213], v163 offset:33792
	ds_read_b128 v[214:217], v163 offset:34816
	ds_read_b128 v[228:231], v163 offset:35840
	ds_read_b128 v[232:235], v163 offset:36864
	ds_read_b128 v[236:239], v163 offset:37888
	ds_read_b128 v[240:243], v163 offset:38912
	ds_read_b128 v[244:247], v163 offset:39936
	global_load_lds_dwordx4 v0, s[30:31]
	s_mov_b32 m0, s50
	s_nop 0
	global_load_lds_dwordx4 v156, s[30:31]
	s_waitcnt vmcnt(8) lgkmcnt(0)
	s_barrier
	v_mfma_f32_16x16x32_bf16 v[130:133], v[164:167], v[206:209], v[130:133]
	v_mfma_f32_16x16x32_bf16 v[126:129], v[172:175], v[206:209], v[126:129]
	v_mfma_f32_16x16x32_bf16 v[114:117], v[164:167], v[214:217], v[114:117]
	v_mfma_f32_16x16x32_bf16 v[110:113], v[172:175], v[214:217], v[110:113]
	v_mfma_f32_16x16x32_bf16 v[98:101], v[164:167], v[232:235], v[98:101]
	v_mfma_f32_16x16x32_bf16 v[94:97], v[172:175], v[232:235], v[94:97]
	v_mfma_f32_16x16x32_bf16 v[82:85], v[164:167], v[240:243], v[82:85]
	v_mfma_f32_16x16x32_bf16 v[78:81], v[172:175], v[240:243], v[78:81]
	v_mfma_f32_16x16x32_bf16 v[130:133], v[168:171], v[210:213], v[130:133]
	v_mfma_f32_16x16x32_bf16 v[126:129], v[176:179], v[210:213], v[126:129]
	v_mfma_f32_16x16x32_bf16 v[114:117], v[168:171], v[228:231], v[114:117]
	v_mfma_f32_16x16x32_bf16 v[110:113], v[176:179], v[228:231], v[110:113]
	v_mfma_f32_16x16x32_bf16 v[98:101], v[168:171], v[236:239], v[98:101]
	v_mfma_f32_16x16x32_bf16 v[94:97], v[176:179], v[236:239], v[94:97]
	v_mfma_f32_16x16x32_bf16 v[82:85], v[168:171], v[244:247], v[82:85]
	v_mfma_f32_16x16x32_bf16 v[78:81], v[176:179], v[244:247], v[78:81]
	v_mfma_f32_16x16x32_bf16 v[122:125], v[180:183], v[206:209], v[122:125]
	v_mfma_f32_16x16x32_bf16 v[118:121], v[198:201], v[206:209], v[118:121]
	v_mfma_f32_16x16x32_bf16 v[106:109], v[180:183], v[214:217], v[106:109]
	v_mfma_f32_16x16x32_bf16 v[102:105], v[198:201], v[214:217], v[102:105]
	v_mfma_f32_16x16x32_bf16 v[90:93], v[180:183], v[232:235], v[90:93]
	v_mfma_f32_16x16x32_bf16 v[86:89], v[198:201], v[232:235], v[86:89]
	v_mfma_f32_16x16x32_bf16 v[74:77], v[180:183], v[240:243], v[74:77]
	v_mfma_f32_16x16x32_bf16 v[70:73], v[198:201], v[240:243], v[70:73]
	v_mfma_f32_16x16x32_bf16 v[122:125], v[194:197], v[210:213], v[122:125]
	v_mfma_f32_16x16x32_bf16 v[118:121], v[202:205], v[210:213], v[118:121]
	v_mfma_f32_16x16x32_bf16 v[106:109], v[194:197], v[228:231], v[106:109]
	v_mfma_f32_16x16x32_bf16 v[102:105], v[202:205], v[228:231], v[102:105]
	v_mfma_f32_16x16x32_bf16 v[90:93], v[194:197], v[236:239], v[90:93]
	v_mfma_f32_16x16x32_bf16 v[86:89], v[202:205], v[236:239], v[86:89]
	v_mfma_f32_16x16x32_bf16 v[74:77], v[194:197], v[244:247], v[74:77]
	v_mfma_f32_16x16x32_bf16 v[70:73], v[202:205], v[244:247], v[70:73]
	s_barrier
	s_add_i32 m0, s45, 0x17f80
	ds_read_b128 v[206:209], v163 offset:49152
	ds_read_b128 v[210:213], v163 offset:50176
	ds_read_b128 v[214:217], v163 offset:51200
	ds_read_b128 v[228:231], v163 offset:52224
	ds_read_b128 v[232:235], v163 offset:53248
	ds_read_b128 v[236:239], v163 offset:54272
	ds_read_b128 v[240:243], v163 offset:55296
	ds_read_b128 v[244:247], v163 offset:56320
	global_load_lds_dwordx4 v[150:151], off offset:128
	s_add_i32 m0, s45, 0x19f80
	global_load_lds_dwordx4 v[184:185], off offset:128
	s_add_i32 m0, s45, 0x1bf80
	s_nop 0
	global_load_lds_dwordx4 v138, s[64:65] offset:128
	s_add_i32 m0, s45, 0x1df80
	s_nop 0
	global_load_lds_dwordx4 v134, s[64:65] offset:128
	s_add_i32 m0, s53, 0xffffff80
	s_nop 0
	global_load_lds_dwordx4 v140, s[30:31] offset:128
	s_add_i32 m0, s54, 0xffffff80
	s_nop 0
	global_load_lds_dwordx4 v136, s[30:31] offset:128
	s_waitcnt vmcnt(8) lgkmcnt(0)
	s_barrier
	v_mfma_f32_16x16x32_bf16 v[66:69], v[164:167], v[206:209], v[66:69]
	v_mfma_f32_16x16x32_bf16 v[62:65], v[172:175], v[206:209], v[62:65]
	v_mfma_f32_16x16x32_bf16 v[50:53], v[164:167], v[214:217], v[50:53]
	v_mfma_f32_16x16x32_bf16 v[46:49], v[172:175], v[214:217], v[46:49]
	v_mfma_f32_16x16x32_bf16 v[34:37], v[164:167], v[232:235], v[34:37]
	v_mfma_f32_16x16x32_bf16 v[30:33], v[172:175], v[232:235], v[30:33]
	v_mfma_f32_16x16x32_bf16 v[18:21], v[164:167], v[240:243], v[18:21]
	v_mfma_f32_16x16x32_bf16 v[14:17], v[172:175], v[240:243], v[14:17]
	v_mfma_f32_16x16x32_bf16 v[66:69], v[168:171], v[210:213], v[66:69]
	v_mfma_f32_16x16x32_bf16 v[62:65], v[176:179], v[210:213], v[62:65]
	v_mfma_f32_16x16x32_bf16 v[50:53], v[168:171], v[228:231], v[50:53]
	v_mfma_f32_16x16x32_bf16 v[46:49], v[176:179], v[228:231], v[46:49]
	v_mfma_f32_16x16x32_bf16 v[34:37], v[168:171], v[236:239], v[34:37]
	v_mfma_f32_16x16x32_bf16 v[30:33], v[176:179], v[236:239], v[30:33]
	v_mfma_f32_16x16x32_bf16 v[18:21], v[168:171], v[244:247], v[18:21]
	v_mfma_f32_16x16x32_bf16 v[14:17], v[176:179], v[244:247], v[14:17]
	v_mfma_f32_16x16x32_bf16 v[58:61], v[180:183], v[206:209], v[58:61]
	v_mfma_f32_16x16x32_bf16 v[54:57], v[198:201], v[206:209], v[54:57]
	v_mfma_f32_16x16x32_bf16 v[42:45], v[180:183], v[214:217], v[42:45]
	v_mfma_f32_16x16x32_bf16 v[38:41], v[198:201], v[214:217], v[38:41]
	v_mfma_f32_16x16x32_bf16 v[26:29], v[180:183], v[232:235], v[26:29]
	v_mfma_f32_16x16x32_bf16 v[22:25], v[198:201], v[232:235], v[22:25]
	v_mfma_f32_16x16x32_bf16 v[10:13], v[180:183], v[240:243], v[10:13]
	v_mfma_f32_16x16x32_bf16 v[6:9], v[198:201], v[240:243], v[6:9]
	v_mfma_f32_16x16x32_bf16 v[58:61], v[194:197], v[210:213], v[58:61]
	v_mfma_f32_16x16x32_bf16 v[54:57], v[202:205], v[210:213], v[54:57]
	v_mfma_f32_16x16x32_bf16 v[42:45], v[194:197], v[228:231], v[42:45]
	v_mfma_f32_16x16x32_bf16 v[38:41], v[202:205], v[228:231], v[38:41]
	v_mfma_f32_16x16x32_bf16 v[26:29], v[194:197], v[236:239], v[26:29]
	v_mfma_f32_16x16x32_bf16 v[22:25], v[202:205], v[236:239], v[22:25]
	v_mfma_f32_16x16x32_bf16 v[10:13], v[194:197], v[244:247], v[10:13]
	v_mfma_f32_16x16x32_bf16 v[6:9], v[202:205], v[244:247], v[6:9]
	s_barrier
	s_add_u32 s28, s28, 0x100
	s_addc_u32 s29, s29, 0
	s_add_u32 s41, s41, 0x100
	s_addc_u32 s62, s62, 0
	s_cmp_ge_i32 s63, s55
	s_mov_b32 s30, s63
	s_cbranch_scc0 .LBB0_1074
	v_readlane_b32 s67, v255, 30

; #define PG8_STAGE(bufoff, gbase, voff) do { _Pragma("unroll") for (int _i = 0; _i < 2; ++_i) \
;         __builtin_amdgcn_global_load_lds((const unsigned*)((const char*)(gbase) + (voff)[_i]), (PG8_LAS unsigned*)(lds + (bufoff) + ldsw + _i * 8192), 16, 0, 0); } while (0)
; #define PG8_LDA(dst, b, h) do { _Pragma("unroll") for (int m = 0; m < 4; ++m) _Pragma("unroll") for (int k = 0; k < 2; ++k) dst[m][k] = *(const PG8_LAS bf16x8*)(lds + PG8_SA(b, h) + aoff + m * 2048 + k * 1024); } while (0)
; #define PG8_LDB(dst, b, h) do { _Pragma("unroll") for (int n = 0; n < 2; ++n) _Pragma("unroll") for (int k = 0; k < 2; ++k) dst[n][k] = *(const PG8_LAS bf16x8*)(lds + PG8_SB(b, h) + boff + n * 2048 + k * 1024); } while (0)
; #define PG8_MMA(ai, bj, At, Bt) do { __builtin_amdgcn_s_setprio(1); _Pragma("unroll") for (int m = 0; m < 4; ++m) _Pragma("unroll") for (int n = 0; n < 2; ++n) _Pragma("unroll") for (int k = 0; k < 2; ++k) \
;         acc[ai][bj][m][n] = __builtin_amdgcn_mfma_f32_16x16x32_bf16(Bt[n][k], At[m][k], acc[ai][bj][m][n], 0, 0, 0); __builtin_amdgcn_s_setprio(0); } while (0)
; #define PG8_WAIT_V(n) asm volatile("s_waitcnt vmcnt(" #n ")" ::: "memory")
; #define PG8_WAIT_L(n) asm volatile("s_waitcnt lgkmcnt(" #n ")" ::: "memory")
; template <class Epi, class Sched, bool ALIGN_EPI = false, bool SP2 = false>
; __device__ __forceinline__ void gemm_phase(PG8_LAS unsigned char* lds, const Gemm g, const Sched& S, const Epi& E, const int wv) {
;     ...
;             const bool last = (t == nt - 2);
;             const char* a1 = cA + (size_t)(t + 1) * kstep;
;             const char* a2 = last ? nA : cA + (size_t)(t + 2) * kstep; const char* b2 = last ? nB : cB + (size_t)(t + 2) * kstep;
;             const char* a3 = a2 + kstep; const char* b3 = b2 + kstep;
;             if (last && has_next) S.a_ready(nxt);
;             if constexpr (SP2) {
;             PG8_LDB(B0, 0, 0); PG8_LDB(B1, 0, 1); PG8_SCHED; PG8_LDA(At, 0, 0); PG8_STAGE(PG8_SA(1, 1), a1 + hstepA, voffA);
;             PG8_WAIT_V(8); PG8_WAIT_L(0); PG8_BAR; PG8_MMA(0, 0, At, B0); PG8_MMA(0, 1, At, B1); PG8_BAR; PG8_SCHED;
;             PG8_LDA(At, 0, 1); PG8_STAGE(PG8_SB(0, 0), b2, voffB); PG8_STAGE(PG8_SB(0, 1), b2 + hstepB, voffB); PG8_STAGE(PG8_SA(0, 0), a2, voffA);
;             PG8_WAIT_V(8); PG8_WAIT_L(0); PG8_BAR; PG8_MMA(1, 0, At, B0); PG8_MMA(1, 1, At, B1); PG8_BAR; PG8_SCHED;
.LBB0_1495:
	s_add_i32 s52, s46, 2
	s_add_u32 s14, s48, 0x100
	s_addc_u32 s15, s49, 0
	s_cmp_eq_u32 s72, s46
	s_cselect_b32 s47, s11, s15
	s_cselect_b32 s46, s13, s14
	s_cselect_b32 s77, s87, s51
	s_cselect_b32 s76, s86, s35
	ds_read_b128 v[138:141], v192
	ds_read_b128 v[142:145], v192 offset:1024
	ds_read_b128 v[146:149], v192 offset:2048
	ds_read_b128 v[150:153], v192 offset:3072
	ds_read_b128 v[154:157], v193
	ds_read_b128 v[158:161], v193 offset:1024
	ds_read_b128 v[162:165], v193 offset:2048
	ds_read_b128 v[166:169], v193 offset:3072
	s_add_i32 m0, s64, 0xc000
	ds_read_b128 v[194:197], v211
	ds_read_b128 v[198:201], v211 offset:1024
	ds_read_b128 v[202:205], v211 offset:2048
	ds_read_b128 v[214:217], v211 offset:3072
	ds_read_b128 v[228:231], v211 offset:4096
	ds_read_b128 v[232:235], v211 offset:5120
	ds_read_b128 v[236:239], v211 offset:6144
	ds_read_b128 v[240:243], v211 offset:7168
	global_load_lds_dwordx4 v182, s[48:49]
	v_lshl_add_u64 v[190:191], s[48:49], 0, v[184:185]
	s_add_i32 m0, s64, 0xe000
	s_nop 0
	global_load_lds_dwordx4 v[190:191], off
	s_waitcnt vmcnt(8) lgkmcnt(0)
	s_barrier
	v_mfma_f32_16x16x32_bf16 v[118:121], v[138:141], v[194:197], v[118:121]
	v_mfma_f32_16x16x32_bf16 v[46:49], v[146:149], v[194:197], v[46:49]
	v_mfma_f32_16x16x32_bf16 v[110:113], v[138:141], v[202:205], v[110:113]
	v_mfma_f32_16x16x32_bf16 v[38:41], v[146:149], v[202:205], v[38:41]
	v_mfma_f32_16x16x32_bf16 v[134:137], v[138:141], v[228:231], v[134:137]
	v_mfma_f32_16x16x32_bf16 v[62:65], v[146:149], v[228:231], v[62:65]
	v_mfma_f32_16x16x32_bf16 v[130:133], v[138:141], v[236:239], v[130:133]
	v_mfma_f32_16x16x32_bf16 v[58:61], v[146:149], v[236:239], v[58:61]
	v_mfma_f32_16x16x32_bf16 v[118:121], v[142:145], v[198:201], v[118:121]
	v_mfma_f32_16x16x32_bf16 v[46:49], v[150:153], v[198:201], v[46:49]
	v_mfma_f32_16x16x32_bf16 v[110:113], v[142:145], v[214:217], v[110:113]
	v_mfma_f32_16x16x32_bf16 v[38:41], v[150:153], v[214:217], v[38:41]
	v_mfma_f32_16x16x32_bf16 v[134:137], v[142:145], v[232:235], v[134:137]
	v_mfma_f32_16x16x32_bf16 v[62:65], v[150:153], v[232:235], v[62:65]
	v_mfma_f32_16x16x32_bf16 v[130:133], v[142:145], v[240:243], v[130:133]
	v_mfma_f32_16x16x32_bf16 v[58:61], v[150:153], v[240:243], v[58:61]
	v_mfma_f32_16x16x32_bf16 v[114:117], v[154:157], v[194:197], v[114:117]
	v_mfma_f32_16x16x32_bf16 v[42:45], v[162:165], v[194:197], v[42:45]
	v_mfma_f32_16x16x32_bf16 v[106:109], v[154:157], v[202:205], v[106:109]
	v_mfma_f32_16x16x32_bf16 v[34:37], v[162:165], v[202:205], v[34:37]
	v_mfma_f32_16x16x32_bf16 v[126:129], v[154:157], v[228:231], v[126:129]
	v_mfma_f32_16x16x32_bf16 v[54:57], v[162:165], v[228:231], v[54:57]
	v_mfma_f32_16x16x32_bf16 v[122:125], v[154:157], v[236:239], v[122:125]
	v_mfma_f32_16x16x32_bf16 v[50:53], v[162:165], v[236:239], v[50:53]
	v_mfma_f32_16x16x32_bf16 v[114:117], v[158:161], v[198:201], v[114:117]
	v_mfma_f32_16x16x32_bf16 v[42:45], v[166:169], v[198:201], v[42:45]
	v_mfma_f32_16x16x32_bf16 v[106:109], v[158:161], v[214:217], v[106:109]
	v_mfma_f32_16x16x32_bf16 v[34:37], v[166:169], v[214:217], v[34:37]
	v_mfma_f32_16x16x32_bf16 v[126:129], v[158:161], v[232:235], v[126:129]
	v_mfma_f32_16x16x32_bf16 v[54:57], v[166:169], v[232:235], v[54:57]
	v_mfma_f32_16x16x32_bf16 v[122:125], v[158:161], v[240:243], v[122:125]
	v_mfma_f32_16x16x32_bf16 v[50:53], v[166:169], v[240:243], v[50:53]
	s_barrier
	s_add_i32 m0, s63, 0x10000
	ds_read_b128 v[194:197], v211 offset:16384
	ds_read_b128 v[198:201], v211 offset:17408
	ds_read_b128 v[202:205], v211 offset:18432
	ds_read_b128 v[214:217], v211 offset:19456
	ds_read_b128 v[228:231], v211 offset:20480
	ds_read_b128 v[232:235], v211 offset:21504
	ds_read_b128 v[236:239], v211 offset:22528
	ds_read_b128 v[240:243], v211 offset:23552
	global_load_lds_dwordx4 v0, s[76:77]
	s_add_i32 m0, s63, 0x12000
	s_add_u32 s48, s76, s16
	s_addc_u32 s49, s77, s17
	s_add_i32 s53, s63, 0x14000
	global_load_lds_dwordx4 v174, s[76:77]
	s_mov_b32 m0, s53
	global_load_lds_dwordx4 v0, s[48:49]
	s_add_i32 m0, s53, 0x2000
	global_load_lds_dwordx4 v174, s[48:49]
	s_mov_b32 m0, s64
	global_load_lds_dwordx4 v170, s[46:47]
	s_mov_b32 m0, s65
	s_nop 0
	global_load_lds_dwordx4 v172, s[46:47]
	s_waitcnt vmcnt(8) lgkmcnt(0)
	s_barrier
	v_mfma_f32_16x16x32_bf16 v[86:89], v[138:141], v[194:197], v[86:89]
	v_mfma_f32_16x16x32_bf16 v[14:17], v[146:149], v[194:197], v[14:17]
	v_mfma_f32_16x16x32_bf16 v[70:73], v[138:141], v[202:205], v[70:73]
	v_mfma_f32_16x16x32_bf16 v[6:9], v[146:149], v[202:205], v[6:9]
	v_mfma_f32_16x16x32_bf16 v[102:105], v[138:141], v[228:231], v[102:105]
	v_mfma_f32_16x16x32_bf16 v[30:33], v[146:149], v[228:231], v[30:33]
	v_mfma_f32_16x16x32_bf16 v[98:101], v[138:141], v[236:239], v[98:101]
	v_mfma_f32_16x16x32_bf16 v[26:29], v[146:149], v[236:239], v[26:29]
	v_mfma_f32_16x16x32_bf16 v[86:89], v[142:145], v[198:201], v[86:89]
	v_mfma_f32_16x16x32_bf16 v[14:17], v[150:153], v[198:201], v[14:17]
	v_mfma_f32_16x16x32_bf16 v[70:73], v[142:145], v[214:217], v[70:73]
	v_mfma_f32_16x16x32_bf16 v[6:9], v[150:153], v[214:217], v[6:9]
	v_mfma_f32_16x16x32_bf16 v[102:105], v[142:145], v[232:235], v[102:105]
	v_mfma_f32_16x16x32_bf16 v[30:33], v[150:153], v[232:235], v[30:33]
	v_mfma_f32_16x16x32_bf16 v[98:101], v[142:145], v[240:243], v[98:101]
	v_mfma_f32_16x16x32_bf16 v[26:29], v[150:153], v[240:243], v[26:29]
	v_mfma_f32_16x16x32_bf16 v[82:85], v[154:157], v[194:197], v[82:85]
	v_mfma_f32_16x16x32_bf16 v[10:13], v[162:165], v[194:197], v[10:13]
	v_mfma_f32_16x16x32_bf16 v[66:69], v[154:157], v[202:205], v[66:69]
	v_mfma_f32_16x16x32_bf16 v[2:5], v[162:165], v[202:205], v[2:5]
	v_mfma_f32_16x16x32_bf16 v[94:97], v[154:157], v[228:231], v[94:97]
	v_mfma_f32_16x16x32_bf16 v[22:25], v[162:165], v[228:231], v[22:25]
	v_mfma_f32_16x16x32_bf16 v[90:93], v[154:157], v[236:239], v[90:93]
	v_mfma_f32_16x16x32_bf16 v[18:21], v[162:165], v[236:239], v[18:21]
	v_mfma_f32_16x16x32_bf16 v[82:85], v[158:161], v[198:201], v[82:85]
	v_mfma_f32_16x16x32_bf16 v[10:13], v[166:169], v[198:201], v[10:13]
	v_mfma_f32_16x16x32_bf16 v[66:69], v[158:161], v[214:217], v[66:69]
	v_mfma_f32_16x16x32_bf16 v[2:5], v[166:169], v[214:217], v[2:5]
	v_mfma_f32_16x16x32_bf16 v[94:97], v[158:161], v[232:235], v[94:97]
	v_mfma_f32_16x16x32_bf16 v[22:25], v[166:169], v[232:235], v[22:25]
	v_mfma_f32_16x16x32_bf16 v[90:93], v[158:161], v[240:243], v[90:93]
	v_mfma_f32_16x16x32_bf16 v[18:21], v[166:169], v[240:243], v[18:21]
	s_barrier
; #define PG8_STAGE(bufoff, gbase, voff) do { _Pragma("unroll") for (int _i = 0; _i < 2; ++_i) \
;         __builtin_amdgcn_global_load_lds((const unsigned*)((const char*)(gbase) + (voff)[_i]), (PG8_LAS unsigned*)(lds + (bufoff) + ldsw + _i * 8192), 16, 0, 0); } while (0)
; #define PG8_LDA(dst, b, h) do { _Pragma("unroll") for (int m = 0; m < 4; ++m) _Pragma("unroll") for (int k = 0; k < 2; ++k) dst[m][k] = *(const PG8_LAS bf16x8*)(lds + PG8_SA(b, h) + aoff + m * 2048 + k * 1024); } while (0)
; #define PG8_LDB(dst, b, h) do { _Pragma("unroll") for (int n = 0; n < 2; ++n) _Pragma("unroll") for (int k = 0; k < 2; ++k) dst[n][k] = *(const PG8_LAS bf16x8*)(lds + PG8_SB(b, h) + boff + n * 2048 + k * 1024); } while (0)
; #define PG8_MMA(ai, bj, At, Bt) do { __builtin_amdgcn_s_setprio(1); _Pragma("unroll") for (int m = 0; m < 4; ++m) _Pragma("unroll") for (int n = 0; n < 2; ++n) _Pragma("unroll") for (int k = 0; k < 2; ++k) \
;         acc[ai][bj][m][n] = __builtin_amdgcn_mfma_f32_16x16x32_bf16(Bt[n][k], At[m][k], acc[ai][bj][m][n], 0, 0, 0); __builtin_amdgcn_s_setprio(0); } while (0)
; #define PG8_WAIT_V(n) asm volatile("s_waitcnt vmcnt(" #n ")" ::: "memory")
; #define PG8_WAIT_L(n) asm volatile("s_waitcnt lgkmcnt(" #n ")" ::: "memory")
; template <class Epi, class Sched, bool ALIGN_EPI = false, bool SP2 = false>
; __device__ __forceinline__ void gemm_phase(PG8_LAS unsigned char* lds, const Gemm g, const Sched& S, const Epi& E, const int wv) {
;     ...
;         for (int t = 0; t < nt; t += 2) {
;             const bool last = (t == nt - 2);
;             const char* a1 = cA + (size_t)(t + 1) * kstep;
;             const char* a2 = last ? nA : cA + (size_t)(t + 2) * kstep; const char* b2 = last ? nB : cB + (size_t)(t + 2) * kstep;
;             const char* a3 = a2 + kstep; const char* b3 = b2 + kstep;
;             if (last && has_next) S.a_ready(nxt);
;     ...
;             PG8_LDB(B0, 1, 0); PG8_LDB(B1, 1, 1); PG8_SCHED; PG8_LDA(At, 1, 0); PG8_STAGE(PG8_SA(0, 1), a2 + hstepA, voffA);
;             PG8_WAIT_V(8); PG8_WAIT_L(0); PG8_BAR; PG8_MMA(0, 0, At, B0); PG8_MMA(0, 1, At, B1); PG8_BAR; PG8_SCHED;
;             PG8_LDA(At, 1, 1); PG8_STAGE(PG8_SB(1, 0), b3, voffB); PG8_STAGE(PG8_SB(1, 1), b3 + hstepB, voffB); PG8_STAGE(PG8_SA(1, 0), a3, voffA);
;             PG8_WAIT_V(8); PG8_WAIT_L(0); PG8_BAR; PG8_MMA(1, 0, At, B0); PG8_MMA(1, 1, At, B1); PG8_BAR; PG8_SCHED;
	ds_read_b128 v[138:141], v213
	ds_read_b128 v[142:145], v213 offset:1024
	ds_read_b128 v[146:149], v213 offset:2048
	ds_read_b128 v[150:153], v213 offset:3072
	ds_read_b128 v[154:157], v227
	ds_read_b128 v[158:161], v227 offset:1024
	ds_read_b128 v[162:165], v227 offset:2048
	ds_read_b128 v[166:169], v227 offset:3072
	s_mov_b32 m0, s66
	ds_read_b128 v[194:197], v211 offset:32768
	ds_read_b128 v[198:201], v211 offset:33792
	ds_read_b128 v[202:205], v211 offset:34816
	ds_read_b128 v[214:217], v211 offset:35840
	ds_read_b128 v[228:231], v211 offset:36864
	ds_read_b128 v[232:235], v211 offset:37888
	ds_read_b128 v[236:239], v211 offset:38912
	ds_read_b128 v[240:243], v211 offset:39936
	global_load_lds_dwordx4 v218, s[46:47]
	s_mov_b32 m0, s67
	s_nop 0
	global_load_lds_dwordx4 v219, s[46:47]
	s_waitcnt vmcnt(8) lgkmcnt(0)
	s_barrier
	v_mfma_f32_16x16x32_bf16 v[118:121], v[138:141], v[194:197], v[118:121]
	v_mfma_f32_16x16x32_bf16 v[46:49], v[146:149], v[194:197], v[46:49]
	v_mfma_f32_16x16x32_bf16 v[110:113], v[138:141], v[202:205], v[110:113]
	v_mfma_f32_16x16x32_bf16 v[38:41], v[146:149], v[202:205], v[38:41]
	v_mfma_f32_16x16x32_bf16 v[134:137], v[138:141], v[228:231], v[134:137]
	v_mfma_f32_16x16x32_bf16 v[62:65], v[146:149], v[228:231], v[62:65]
	v_mfma_f32_16x16x32_bf16 v[130:133], v[138:141], v[236:239], v[130:133]
	v_mfma_f32_16x16x32_bf16 v[58:61], v[146:149], v[236:239], v[58:61]
	v_mfma_f32_16x16x32_bf16 v[118:121], v[142:145], v[198:201], v[118:121]
	v_mfma_f32_16x16x32_bf16 v[46:49], v[150:153], v[198:201], v[46:49]
	v_mfma_f32_16x16x32_bf16 v[110:113], v[142:145], v[214:217], v[110:113]
	v_mfma_f32_16x16x32_bf16 v[38:41], v[150:153], v[214:217], v[38:41]
	v_mfma_f32_16x16x32_bf16 v[134:137], v[142:145], v[232:235], v[134:137]
	v_mfma_f32_16x16x32_bf16 v[62:65], v[150:153], v[232:235], v[62:65]
	v_mfma_f32_16x16x32_bf16 v[130:133], v[142:145], v[240:243], v[130:133]
	v_mfma_f32_16x16x32_bf16 v[58:61], v[150:153], v[240:243], v[58:61]
	v_mfma_f32_16x16x32_bf16 v[114:117], v[154:157], v[194:197], v[114:117]
	v_mfma_f32_16x16x32_bf16 v[42:45], v[162:165], v[194:197], v[42:45]
	v_mfma_f32_16x16x32_bf16 v[106:109], v[154:157], v[202:205], v[106:109]
	v_mfma_f32_16x16x32_bf16 v[34:37], v[162:165], v[202:205], v[34:37]
	v_mfma_f32_16x16x32_bf16 v[126:129], v[154:157], v[228:231], v[126:129]
	v_mfma_f32_16x16x32_bf16 v[54:57], v[162:165], v[228:231], v[54:57]
	v_mfma_f32_16x16x32_bf16 v[122:125], v[154:157], v[236:239], v[122:125]
	v_mfma_f32_16x16x32_bf16 v[50:53], v[162:165], v[236:239], v[50:53]
	v_mfma_f32_16x16x32_bf16 v[114:117], v[158:161], v[198:201], v[114:117]
	v_mfma_f32_16x16x32_bf16 v[42:45], v[166:169], v[198:201], v[42:45]
	v_mfma_f32_16x16x32_bf16 v[106:109], v[158:161], v[214:217], v[106:109]
	v_mfma_f32_16x16x32_bf16 v[34:37], v[166:169], v[214:217], v[34:37]
	v_mfma_f32_16x16x32_bf16 v[126:129], v[158:161], v[232:235], v[126:129]
	v_mfma_f32_16x16x32_bf16 v[54:57], v[166:169], v[232:235], v[54:57]
	v_mfma_f32_16x16x32_bf16 v[122:125], v[158:161], v[240:243], v[122:125]
	v_mfma_f32_16x16x32_bf16 v[50:53], v[166:169], v[240:243], v[50:53]
	s_barrier
	s_add_i32 m0, s63, 0x17f80
	ds_read_b128 v[194:197], v211 offset:49152
	ds_read_b128 v[198:201], v211 offset:50176
	ds_read_b128 v[202:205], v211 offset:51200
	ds_read_b128 v[214:217], v211 offset:52224
	ds_read_b128 v[228:231], v211 offset:53248
	ds_read_b128 v[232:235], v211 offset:54272
	ds_read_b128 v[236:239], v211 offset:55296
	ds_read_b128 v[240:243], v211 offset:56320
	global_load_lds_dwordx4 v0, s[76:77] offset:128
	s_add_i32 m0, s63, 0x19f80
	global_load_lds_dwordx4 v174, s[76:77] offset:128
	s_add_i32 m0, s63, 0x1bf80
	s_nop 0
	global_load_lds_dwordx4 v0, s[48:49] offset:128
	s_add_i32 m0, s63, 0x1df80
	s_nop 0
	global_load_lds_dwordx4 v174, s[48:49] offset:128
	s_add_i32 m0, s70, 0xffffff80
	s_nop 0
	global_load_lds_dwordx4 v170, s[46:47] offset:128
	s_add_i32 m0, s71, 0xffffff80
	s_nop 0
	global_load_lds_dwordx4 v172, s[46:47] offset:128
	s_waitcnt vmcnt(8) lgkmcnt(0)
	s_barrier
	v_mfma_f32_16x16x32_bf16 v[86:89], v[138:141], v[194:197], v[86:89]
	v_mfma_f32_16x16x32_bf16 v[14:17], v[146:149], v[194:197], v[14:17]
	v_mfma_f32_16x16x32_bf16 v[70:73], v[138:141], v[202:205], v[70:73]
	v_mfma_f32_16x16x32_bf16 v[6:9], v[146:149], v[202:205], v[6:9]
	v_mfma_f32_16x16x32_bf16 v[102:105], v[138:141], v[228:231], v[102:105]
	v_mfma_f32_16x16x32_bf16 v[30:33], v[146:149], v[228:231], v[30:33]
	v_mfma_f32_16x16x32_bf16 v[98:101], v[138:141], v[236:239], v[98:101]
	v_mfma_f32_16x16x32_bf16 v[26:29], v[146:149], v[236:239], v[26:29]
	v_mfma_f32_16x16x32_bf16 v[86:89], v[142:145], v[198:201], v[86:89]
	v_mfma_f32_16x16x32_bf16 v[14:17], v[150:153], v[198:201], v[14:17]
	v_mfma_f32_16x16x32_bf16 v[70:73], v[142:145], v[214:217], v[70:73]
	v_mfma_f32_16x16x32_bf16 v[6:9], v[150:153], v[214:217], v[6:9]
	v_mfma_f32_16x16x32_bf16 v[102:105], v[142:145], v[232:235], v[102:105]
	v_mfma_f32_16x16x32_bf16 v[30:33], v[150:153], v[232:235], v[30:33]
	v_mfma_f32_16x16x32_bf16 v[98:101], v[142:145], v[240:243], v[98:101]
	v_mfma_f32_16x16x32_bf16 v[26:29], v[150:153], v[240:243], v[26:29]
	v_mfma_f32_16x16x32_bf16 v[82:85], v[154:157], v[194:197], v[82:85]
	v_mfma_f32_16x16x32_bf16 v[10:13], v[162:165], v[194:197], v[10:13]
	v_mfma_f32_16x16x32_bf16 v[66:69], v[154:157], v[202:205], v[66:69]
	v_mfma_f32_16x16x32_bf16 v[2:5], v[162:165], v[202:205], v[2:5]
	v_mfma_f32_16x16x32_bf16 v[94:97], v[154:157], v[228:231], v[94:97]
	v_mfma_f32_16x16x32_bf16 v[22:25], v[162:165], v[228:231], v[22:25]
	v_mfma_f32_16x16x32_bf16 v[90:93], v[154:157], v[236:239], v[90:93]
	v_mfma_f32_16x16x32_bf16 v[18:21], v[162:165], v[236:239], v[18:21]
	v_mfma_f32_16x16x32_bf16 v[82:85], v[158:161], v[198:201], v[82:85]
	v_mfma_f32_16x16x32_bf16 v[10:13], v[166:169], v[198:201], v[10:13]
	v_mfma_f32_16x16x32_bf16 v[66:69], v[158:161], v[214:217], v[66:69]
	v_mfma_f32_16x16x32_bf16 v[2:5], v[166:169], v[214:217], v[2:5]
	v_mfma_f32_16x16x32_bf16 v[94:97], v[158:161], v[232:235], v[94:97]
	v_mfma_f32_16x16x32_bf16 v[22:25], v[166:169], v[232:235], v[22:25]
	v_mfma_f32_16x16x32_bf16 v[90:93], v[158:161], v[240:243], v[90:93]
	v_mfma_f32_16x16x32_bf16 v[18:21], v[166:169], v[240:243], v[18:21]
	s_barrier
	s_add_u32 s35, s35, 0x100
	s_addc_u32 s51, s51, 0
	s_cmp_ge_i32 s52, s68
	s_mov_b64 s[48:49], s[14:15]
	s_mov_b32 s46, s52
	s_cbranch_scc0 .LBB0_1495
	s_movk_i32 s78, 0x7ff
	s_movk_i32 s76, 0x3000
	s_and_b64 vcc, exec, s[30:31]
	s_cbranch_vccz .LBB0_1470

; #define PG8_STAGE(bufoff, gbase, voff) do { _Pragma("unroll") for (int _i = 0; _i < 2; ++_i) \
;         __builtin_amdgcn_global_load_lds((const unsigned*)((const char*)(gbase) + (voff)[_i]), (PG8_LAS unsigned*)(lds + (bufoff) + ldsw + _i * 8192), 16, 0, 0); } while (0)
; #define PG8_LDA(dst, b, h) do { _Pragma("unroll") for (int m = 0; m < 4; ++m) _Pragma("unroll") for (int k = 0; k < 2; ++k) dst[m][k] = *(const PG8_LAS bf16x8*)(lds + PG8_SA(b, h) + aoff + m * 2048 + k * 1024); } while (0)
; #define PG8_LDB(dst, b, h) do { _Pragma("unroll") for (int n = 0; n < 2; ++n) _Pragma("unroll") for (int k = 0; k < 2; ++k) dst[n][k] = *(const PG8_LAS bf16x8*)(lds + PG8_SB(b, h) + boff + n * 2048 + k * 1024); } while (0)
; #define PG8_MMA(ai, bj, At, Bt) do { __builtin_amdgcn_s_setprio(1); _Pragma("unroll") for (int m = 0; m < 4; ++m) _Pragma("unroll") for (int n = 0; n < 2; ++n) _Pragma("unroll") for (int k = 0; k < 2; ++k) \
;         acc[ai][bj][m][n] = __builtin_amdgcn_mfma_f32_16x16x32_bf16(Bt[n][k], At[m][k], acc[ai][bj][m][n], 0, 0, 0); __builtin_amdgcn_s_setprio(0); } while (0)
; #define PG8_WAIT_V(n) asm volatile("s_waitcnt vmcnt(" #n ")" ::: "memory")
; #define PG8_WAIT_L(n) asm volatile("s_waitcnt lgkmcnt(" #n ")" ::: "memory")
; template <class Epi, class Sched, bool ALIGN_EPI = false, bool SP2 = false>
; __device__ __forceinline__ void gemm_phase(PG8_LAS unsigned char* lds, const Gemm g, const Sched& S, const Epi& E, const int wv) {
;     ...
;             const bool last = (t == nt - 2);
;             const char* a1 = cA + (size_t)(t + 1) * kstep;
;             const char* a2 = last ? nA : cA + (size_t)(t + 2) * kstep; const char* b2 = last ? nB : cB + (size_t)(t + 2) * kstep;
;             const char* a3 = a2 + kstep; const char* b3 = b2 + kstep;
;             if (last && has_next) S.a_ready(nxt);
;             if constexpr (SP2) {
;             PG8_LDB(B0, 0, 0); PG8_LDB(B1, 0, 1); PG8_SCHED; PG8_LDA(At, 0, 0); PG8_STAGE(PG8_SA(1, 1), a1 + hstepA, voffA);
;             PG8_WAIT_V(8); PG8_WAIT_L(0); PG8_BAR; PG8_MMA(0, 0, At, B0); PG8_MMA(0, 1, At, B1); PG8_BAR; PG8_SCHED;
;             PG8_LDA(At, 0, 1); PG8_STAGE(PG8_SB(0, 0), b2, voffB); PG8_STAGE(PG8_SB(0, 1), b2 + hstepB, voffB); PG8_STAGE(PG8_SA(0, 0), a2, voffA);
;             PG8_WAIT_V(8); PG8_WAIT_L(0); PG8_BAR; PG8_MMA(1, 0, At, B0); PG8_MMA(1, 1, At, B1); PG8_BAR; PG8_SCHED;
.LBB0_1676:
	s_add_i32 s67, s44, 2
	s_add_u32 s34, s30, 0x100
	s_addc_u32 s35, s31, 0
	s_cmp_eq_u32 s59, s44
	s_cselect_b32 s45, s13, s35
	s_cselect_b32 s44, s12, s34
	s_cselect_b32 s69, s15, s66
	s_cselect_b32 s68, s14, s65
	ds_read_b128 v[114:117], v197
	ds_read_b128 v[126:129], v197 offset:1024
	ds_read_b128 v[138:141], v197 offset:2048
	ds_read_b128 v[142:145], v197 offset:3072
	ds_read_b128 v[146:149], v201
	ds_read_b128 v[150:153], v201 offset:1024
	ds_read_b128 v[154:157], v201 offset:2048
	ds_read_b128 v[158:161], v201 offset:3072
	s_add_i32 m0, s52, 0xc000
	ds_read_b128 v[162:165], v235
	ds_read_b128 v[166:169], v235 offset:1024
	ds_read_b128 v[170:173], v235 offset:2048
	ds_read_b128 v[174:177], v235 offset:3072
	ds_read_b128 v[178:181], v235 offset:4096
	ds_read_b128 v[182:185], v235 offset:5120
	ds_read_b128 v[204:207], v235 offset:6144
	ds_read_b128 v[208:211], v235 offset:7168
	global_load_lds_dwordx4 v200, s[30:31]
	s_add_i32 m0, s52, 0xe000
	s_nop 0
	global_load_lds_dwordx4 v202, s[30:31]
	s_waitcnt vmcnt(8) lgkmcnt(0)
	s_barrier
	v_mfma_f32_16x16x32_bf16 v[134:137], v[114:117], v[162:165], v[134:137]
	v_mfma_f32_16x16x32_bf16 v[130:133], v[138:141], v[162:165], v[130:133]
	v_mfma_f32_16x16x32_bf16 v[110:113], v[114:117], v[170:173], v[110:113]
	v_mfma_f32_16x16x32_bf16 v[106:109], v[138:141], v[170:173], v[106:109]
	v_mfma_f32_16x16x32_bf16 v[94:97], v[114:117], v[178:181], v[94:97]
	v_mfma_f32_16x16x32_bf16 v[90:93], v[138:141], v[178:181], v[90:93]
	v_mfma_f32_16x16x32_bf16 v[78:81], v[114:117], v[204:207], v[78:81]
	v_mfma_f32_16x16x32_bf16 v[74:77], v[138:141], v[204:207], v[74:77]
	v_mfma_f32_16x16x32_bf16 v[134:137], v[126:129], v[166:169], v[134:137]
	v_mfma_f32_16x16x32_bf16 v[130:133], v[142:145], v[166:169], v[130:133]
	v_mfma_f32_16x16x32_bf16 v[110:113], v[126:129], v[174:177], v[110:113]
	v_mfma_f32_16x16x32_bf16 v[106:109], v[142:145], v[174:177], v[106:109]
	v_mfma_f32_16x16x32_bf16 v[94:97], v[126:129], v[182:185], v[94:97]
	v_mfma_f32_16x16x32_bf16 v[90:93], v[142:145], v[182:185], v[90:93]
	v_mfma_f32_16x16x32_bf16 v[78:81], v[126:129], v[208:211], v[78:81]
	v_mfma_f32_16x16x32_bf16 v[74:77], v[142:145], v[208:211], v[74:77]
	v_mfma_f32_16x16x32_bf16 v[122:125], v[146:149], v[162:165], v[122:125]
	v_mfma_f32_16x16x32_bf16 v[118:121], v[154:157], v[162:165], v[118:121]
	v_mfma_f32_16x16x32_bf16 v[102:105], v[146:149], v[170:173], v[102:105]
	v_mfma_f32_16x16x32_bf16 v[98:101], v[154:157], v[170:173], v[98:101]
	v_mfma_f32_16x16x32_bf16 v[86:89], v[146:149], v[178:181], v[86:89]
	v_mfma_f32_16x16x32_bf16 v[82:85], v[154:157], v[178:181], v[82:85]
	v_mfma_f32_16x16x32_bf16 v[70:73], v[146:149], v[204:207], v[70:73]
	v_mfma_f32_16x16x32_bf16 v[66:69], v[154:157], v[204:207], v[66:69]
	v_mfma_f32_16x16x32_bf16 v[122:125], v[150:153], v[166:169], v[122:125]
	v_mfma_f32_16x16x32_bf16 v[118:121], v[158:161], v[166:169], v[118:121]
	v_mfma_f32_16x16x32_bf16 v[102:105], v[150:153], v[174:177], v[102:105]
	v_mfma_f32_16x16x32_bf16 v[98:101], v[158:161], v[174:177], v[98:101]
	v_mfma_f32_16x16x32_bf16 v[86:89], v[150:153], v[182:185], v[86:89]
	v_mfma_f32_16x16x32_bf16 v[82:85], v[158:161], v[182:185], v[82:85]
	v_mfma_f32_16x16x32_bf16 v[70:73], v[150:153], v[208:211], v[70:73]
	v_mfma_f32_16x16x32_bf16 v[66:69], v[158:161], v[208:211], v[66:69]
	s_barrier
	v_lshl_add_u64 v[190:191], s[68:69], 0, v[0:1]
	s_add_i32 m0, s47, 0x10000
	ds_read_b128 v[162:165], v235 offset:16384
	ds_read_b128 v[166:169], v235 offset:17408
	ds_read_b128 v[170:173], v235 offset:18432
	ds_read_b128 v[174:177], v235 offset:19456
	ds_read_b128 v[178:181], v235 offset:20480
	ds_read_b128 v[182:185], v235 offset:21504
	ds_read_b128 v[204:207], v235 offset:22528
	ds_read_b128 v[208:211], v235 offset:23552
	global_load_lds_dwordx4 v[190:191], off
	s_add_i32 m0, s47, 0x12000
	s_add_u32 s30, s68, s2
	v_lshl_add_u64 v[192:193], s[68:69], 0, v[198:199]
	s_addc_u32 s31, s69, s3
	s_add_i32 s68, s47, 0x14000
	global_load_lds_dwordx4 v[192:193], off
	v_lshl_add_u64 v[212:213], s[30:31], 0, v[0:1]
	s_mov_b32 m0, s68
	v_lshl_add_u64 v[214:215], s[30:31], 0, v[198:199]
	global_load_lds_dwordx4 v[212:213], off
	s_add_i32 m0, s68, 0x2000
	global_load_lds_dwordx4 v[214:215], off
	s_mov_b32 m0, s52
	global_load_lds_dwordx4 v194, s[44:45]
	s_mov_b32 m0, s53
	s_nop 0
	global_load_lds_dwordx4 v196, s[44:45]
	s_waitcnt vmcnt(8) lgkmcnt(0)
	s_barrier
	v_mfma_f32_16x16x32_bf16 v[62:65], v[114:117], v[162:165], v[62:65]
	v_mfma_f32_16x16x32_bf16 v[58:61], v[138:141], v[162:165], v[58:61]
	v_mfma_f32_16x16x32_bf16 v[46:49], v[114:117], v[170:173], v[46:49]
	v_mfma_f32_16x16x32_bf16 v[42:45], v[138:141], v[170:173], v[42:45]
	v_mfma_f32_16x16x32_bf16 v[30:33], v[114:117], v[178:181], v[30:33]
	v_mfma_f32_16x16x32_bf16 v[26:29], v[138:141], v[178:181], v[26:29]
	v_mfma_f32_16x16x32_bf16 v[14:17], v[114:117], v[204:207], v[14:17]
	v_mfma_f32_16x16x32_bf16 v[10:13], v[138:141], v[204:207], v[10:13]
	v_mfma_f32_16x16x32_bf16 v[62:65], v[126:129], v[166:169], v[62:65]
	v_mfma_f32_16x16x32_bf16 v[58:61], v[142:145], v[166:169], v[58:61]
	v_mfma_f32_16x16x32_bf16 v[46:49], v[126:129], v[174:177], v[46:49]
	v_mfma_f32_16x16x32_bf16 v[42:45], v[142:145], v[174:177], v[42:45]
	v_mfma_f32_16x16x32_bf16 v[30:33], v[126:129], v[182:185], v[30:33]
	v_mfma_f32_16x16x32_bf16 v[26:29], v[142:145], v[182:185], v[26:29]
	v_mfma_f32_16x16x32_bf16 v[14:17], v[126:129], v[208:211], v[14:17]
	v_mfma_f32_16x16x32_bf16 v[10:13], v[142:145], v[208:211], v[10:13]
	v_mfma_f32_16x16x32_bf16 v[54:57], v[146:149], v[162:165], v[54:57]
	v_mfma_f32_16x16x32_bf16 v[50:53], v[154:157], v[162:165], v[50:53]
	v_mfma_f32_16x16x32_bf16 v[38:41], v[146:149], v[170:173], v[38:41]
	v_mfma_f32_16x16x32_bf16 v[34:37], v[154:157], v[170:173], v[34:37]
	v_mfma_f32_16x16x32_bf16 v[22:25], v[146:149], v[178:181], v[22:25]
	v_mfma_f32_16x16x32_bf16 v[18:21], v[154:157], v[178:181], v[18:21]
	v_mfma_f32_16x16x32_bf16 v[6:9], v[146:149], v[204:207], v[6:9]
	v_mfma_f32_16x16x32_bf16 v[2:5], v[154:157], v[204:207], v[2:5]
	v_mfma_f32_16x16x32_bf16 v[54:57], v[150:153], v[166:169], v[54:57]
	v_mfma_f32_16x16x32_bf16 v[50:53], v[158:161], v[166:169], v[50:53]
	v_mfma_f32_16x16x32_bf16 v[38:41], v[150:153], v[174:177], v[38:41]
	v_mfma_f32_16x16x32_bf16 v[34:37], v[158:161], v[174:177], v[34:37]
	v_mfma_f32_16x16x32_bf16 v[22:25], v[150:153], v[182:185], v[22:25]
	v_mfma_f32_16x16x32_bf16 v[18:21], v[158:161], v[182:185], v[18:21]
	v_mfma_f32_16x16x32_bf16 v[6:9], v[150:153], v[208:211], v[6:9]
	v_mfma_f32_16x16x32_bf16 v[2:5], v[158:161], v[208:211], v[2:5]
	s_barrier
; #define PG8_STAGE(bufoff, gbase, voff) do { _Pragma("unroll") for (int _i = 0; _i < 2; ++_i) \
;         __builtin_amdgcn_global_load_lds((const unsigned*)((const char*)(gbase) + (voff)[_i]), (PG8_LAS unsigned*)(lds + (bufoff) + ldsw + _i * 8192), 16, 0, 0); } while (0)
; #define PG8_LDA(dst, b, h) do { _Pragma("unroll") for (int m = 0; m < 4; ++m) _Pragma("unroll") for (int k = 0; k < 2; ++k) dst[m][k] = *(const PG8_LAS bf16x8*)(lds + PG8_SA(b, h) + aoff + m * 2048 + k * 1024); } while (0)
; #define PG8_LDB(dst, b, h) do { _Pragma("unroll") for (int n = 0; n < 2; ++n) _Pragma("unroll") for (int k = 0; k < 2; ++k) dst[n][k] = *(const PG8_LAS bf16x8*)(lds + PG8_SB(b, h) + boff + n * 2048 + k * 1024); } while (0)
; #define PG8_MMA(ai, bj, At, Bt) do { __builtin_amdgcn_s_setprio(1); _Pragma("unroll") for (int m = 0; m < 4; ++m) _Pragma("unroll") for (int n = 0; n < 2; ++n) _Pragma("unroll") for (int k = 0; k < 2; ++k) \
;         acc[ai][bj][m][n] = __builtin_amdgcn_mfma_f32_16x16x32_bf16(Bt[n][k], At[m][k], acc[ai][bj][m][n], 0, 0, 0); __builtin_amdgcn_s_setprio(0); } while (0)
; #define PG8_WAIT_V(n) asm volatile("s_waitcnt vmcnt(" #n ")" ::: "memory")
; #define PG8_WAIT_L(n) asm volatile("s_waitcnt lgkmcnt(" #n ")" ::: "memory")
; #define PG8_BAR __builtin_amdgcn_s_barrier()
; #define PG8_SCHED __builtin_amdgcn_sched_barrier(0)
; template <class Epi, class Sched, bool ALIGN_EPI = false, bool SP2 = false>
; __device__ __forceinline__ void gemm_phase(PG8_LAS unsigned char* lds, const Gemm g, const Sched& S, const Epi& E, const int wv) {
;     ...
;             PG8_LDB(B0, 1, 0); PG8_LDB(B1, 1, 1); PG8_SCHED; PG8_LDA(At, 1, 0); PG8_STAGE(PG8_SA(0, 1), a2 + hstepA, voffA);
;             PG8_WAIT_V(8); PG8_WAIT_L(0); PG8_BAR; PG8_MMA(0, 0, At, B0); PG8_MMA(0, 1, At, B1); PG8_BAR; PG8_SCHED;
;             PG8_LDA(At, 1, 1); PG8_STAGE(PG8_SB(1, 0), b3, voffB); PG8_STAGE(PG8_SB(1, 1), b3 + hstepB, voffB); PG8_STAGE(PG8_SA(1, 0), a3, voffA);
;             PG8_WAIT_V(8); PG8_WAIT_L(0); PG8_BAR; PG8_MMA(1, 0, At, B0); PG8_MMA(1, 1, At, B1); PG8_BAR; PG8_SCHED;
	ds_read_b128 v[114:117], v203
	ds_read_b128 v[126:129], v203 offset:1024
	ds_read_b128 v[138:141], v203 offset:2048
	ds_read_b128 v[142:145], v203 offset:3072
	ds_read_b128 v[146:149], v216
	ds_read_b128 v[150:153], v216 offset:1024
	ds_read_b128 v[154:157], v216 offset:2048
	ds_read_b128 v[158:161], v216 offset:3072
	s_add_u32 s30, s44, 0x180000
	s_addc_u32 s31, s45, 0
	s_mov_b32 m0, s54
	ds_read_b128 v[162:165], v235 offset:32768
	ds_read_b128 v[166:169], v235 offset:33792
	ds_read_b128 v[170:173], v235 offset:34816
	ds_read_b128 v[174:177], v235 offset:35840
	ds_read_b128 v[178:181], v235 offset:36864
	ds_read_b128 v[182:185], v235 offset:37888
	ds_read_b128 v[204:207], v235 offset:38912
	ds_read_b128 v[208:211], v235 offset:39936
	global_load_lds_dwordx4 v194, s[30:31]
	s_mov_b32 m0, s55
	s_nop 0
	global_load_lds_dwordx4 v196, s[30:31]
	s_waitcnt vmcnt(8) lgkmcnt(0)
	s_barrier
	v_mfma_f32_16x16x32_bf16 v[134:137], v[114:117], v[162:165], v[134:137]
	v_mfma_f32_16x16x32_bf16 v[130:133], v[138:141], v[162:165], v[130:133]
	v_mfma_f32_16x16x32_bf16 v[110:113], v[114:117], v[170:173], v[110:113]
	v_mfma_f32_16x16x32_bf16 v[106:109], v[138:141], v[170:173], v[106:109]
	v_mfma_f32_16x16x32_bf16 v[94:97], v[114:117], v[178:181], v[94:97]
	v_mfma_f32_16x16x32_bf16 v[90:93], v[138:141], v[178:181], v[90:93]
	v_mfma_f32_16x16x32_bf16 v[78:81], v[114:117], v[204:207], v[78:81]
	v_mfma_f32_16x16x32_bf16 v[74:77], v[138:141], v[204:207], v[74:77]
	v_mfma_f32_16x16x32_bf16 v[134:137], v[126:129], v[166:169], v[134:137]
	v_mfma_f32_16x16x32_bf16 v[130:133], v[142:145], v[166:169], v[130:133]
	v_mfma_f32_16x16x32_bf16 v[110:113], v[126:129], v[174:177], v[110:113]
	v_mfma_f32_16x16x32_bf16 v[106:109], v[142:145], v[174:177], v[106:109]
	v_mfma_f32_16x16x32_bf16 v[94:97], v[126:129], v[182:185], v[94:97]
	v_mfma_f32_16x16x32_bf16 v[90:93], v[142:145], v[182:185], v[90:93]
	v_mfma_f32_16x16x32_bf16 v[78:81], v[126:129], v[208:211], v[78:81]
	v_mfma_f32_16x16x32_bf16 v[74:77], v[142:145], v[208:211], v[74:77]
	v_mfma_f32_16x16x32_bf16 v[122:125], v[146:149], v[162:165], v[122:125]
	v_mfma_f32_16x16x32_bf16 v[118:121], v[154:157], v[162:165], v[118:121]
	v_mfma_f32_16x16x32_bf16 v[102:105], v[146:149], v[170:173], v[102:105]
	v_mfma_f32_16x16x32_bf16 v[98:101], v[154:157], v[170:173], v[98:101]
	v_mfma_f32_16x16x32_bf16 v[86:89], v[146:149], v[178:181], v[86:89]
	v_mfma_f32_16x16x32_bf16 v[82:85], v[154:157], v[178:181], v[82:85]
	v_mfma_f32_16x16x32_bf16 v[70:73], v[146:149], v[204:207], v[70:73]
	v_mfma_f32_16x16x32_bf16 v[66:69], v[154:157], v[204:207], v[66:69]
	v_mfma_f32_16x16x32_bf16 v[122:125], v[150:153], v[166:169], v[122:125]
	v_mfma_f32_16x16x32_bf16 v[118:121], v[158:161], v[166:169], v[118:121]
	v_mfma_f32_16x16x32_bf16 v[102:105], v[150:153], v[174:177], v[102:105]
	v_mfma_f32_16x16x32_bf16 v[98:101], v[158:161], v[174:177], v[98:101]
	v_mfma_f32_16x16x32_bf16 v[86:89], v[150:153], v[182:185], v[86:89]
	v_mfma_f32_16x16x32_bf16 v[82:85], v[158:161], v[182:185], v[82:85]
	v_mfma_f32_16x16x32_bf16 v[70:73], v[150:153], v[208:211], v[70:73]
	v_mfma_f32_16x16x32_bf16 v[66:69], v[158:161], v[208:211], v[66:69]
	s_barrier
	s_add_i32 m0, s47, 0x17f80
	ds_read_b128 v[162:165], v235 offset:49152
	ds_read_b128 v[166:169], v235 offset:50176
	ds_read_b128 v[170:173], v235 offset:51200
	ds_read_b128 v[174:177], v235 offset:52224
	ds_read_b128 v[178:181], v235 offset:53248
	ds_read_b128 v[182:185], v235 offset:54272
	ds_read_b128 v[204:207], v235 offset:55296
	ds_read_b128 v[208:211], v235 offset:56320
	global_load_lds_dwordx4 v[190:191], off offset:128
	s_add_i32 m0, s47, 0x19f80
	global_load_lds_dwordx4 v[192:193], off offset:128
	s_add_i32 m0, s47, 0x1bf80
	s_nop 0
	global_load_lds_dwordx4 v[212:213], off offset:128
	s_add_i32 m0, s47, 0x1df80
	s_nop 0
	global_load_lds_dwordx4 v[214:215], off offset:128
	s_add_i32 m0, s57, 0xffffff80
	s_nop 0
	global_load_lds_dwordx4 v194, s[44:45] offset:128
	s_add_i32 m0, s58, 0xffffff80
	s_nop 0
	global_load_lds_dwordx4 v196, s[44:45] offset:128
	s_waitcnt vmcnt(8) lgkmcnt(0)
	s_barrier
	v_mfma_f32_16x16x32_bf16 v[62:65], v[114:117], v[162:165], v[62:65]
	v_mfma_f32_16x16x32_bf16 v[58:61], v[138:141], v[162:165], v[58:61]
	v_mfma_f32_16x16x32_bf16 v[46:49], v[114:117], v[170:173], v[46:49]
	v_mfma_f32_16x16x32_bf16 v[42:45], v[138:141], v[170:173], v[42:45]
	v_mfma_f32_16x16x32_bf16 v[30:33], v[114:117], v[178:181], v[30:33]
	v_mfma_f32_16x16x32_bf16 v[26:29], v[138:141], v[178:181], v[26:29]
	v_mfma_f32_16x16x32_bf16 v[14:17], v[114:117], v[204:207], v[14:17]
	v_mfma_f32_16x16x32_bf16 v[10:13], v[138:141], v[204:207], v[10:13]
	v_mfma_f32_16x16x32_bf16 v[62:65], v[126:129], v[166:169], v[62:65]
	v_mfma_f32_16x16x32_bf16 v[58:61], v[142:145], v[166:169], v[58:61]
	v_mfma_f32_16x16x32_bf16 v[46:49], v[126:129], v[174:177], v[46:49]
	v_mfma_f32_16x16x32_bf16 v[42:45], v[142:145], v[174:177], v[42:45]
	v_mfma_f32_16x16x32_bf16 v[30:33], v[126:129], v[182:185], v[30:33]
	v_mfma_f32_16x16x32_bf16 v[26:29], v[142:145], v[182:185], v[26:29]
	v_mfma_f32_16x16x32_bf16 v[14:17], v[126:129], v[208:211], v[14:17]
	v_mfma_f32_16x16x32_bf16 v[10:13], v[142:145], v[208:211], v[10:13]
	v_mfma_f32_16x16x32_bf16 v[54:57], v[146:149], v[162:165], v[54:57]
	v_mfma_f32_16x16x32_bf16 v[50:53], v[154:157], v[162:165], v[50:53]
	v_mfma_f32_16x16x32_bf16 v[38:41], v[146:149], v[170:173], v[38:41]
	v_mfma_f32_16x16x32_bf16 v[34:37], v[154:157], v[170:173], v[34:37]
	v_mfma_f32_16x16x32_bf16 v[22:25], v[146:149], v[178:181], v[22:25]
	v_mfma_f32_16x16x32_bf16 v[18:21], v[154:157], v[178:181], v[18:21]
	v_mfma_f32_16x16x32_bf16 v[6:9], v[146:149], v[204:207], v[6:9]
	v_mfma_f32_16x16x32_bf16 v[2:5], v[154:157], v[204:207], v[2:5]
	v_mfma_f32_16x16x32_bf16 v[54:57], v[150:153], v[166:169], v[54:57]
	v_mfma_f32_16x16x32_bf16 v[50:53], v[158:161], v[166:169], v[50:53]
	v_mfma_f32_16x16x32_bf16 v[38:41], v[150:153], v[174:177], v[38:41]
	v_mfma_f32_16x16x32_bf16 v[34:37], v[158:161], v[174:177], v[34:37]
	v_mfma_f32_16x16x32_bf16 v[22:25], v[150:153], v[182:185], v[22:25]
	v_mfma_f32_16x16x32_bf16 v[18:21], v[158:161], v[182:185], v[18:21]
	v_mfma_f32_16x16x32_bf16 v[6:9], v[150:153], v[208:211], v[6:9]
	v_mfma_f32_16x16x32_bf16 v[2:5], v[158:161], v[208:211], v[2:5]
	s_barrier
	s_add_u32 s65, s65, 0x100
	s_addc_u32 s66, s66, 0
	s_cmp_ge_i32 s67, s56
	s_mov_b64 s[30:31], s[34:35]
	s_mov_b32 s44, s67
	s_cbranch_scc0 .LBB0_1676
	s_movk_i32 s68, 0x4000
	s_movk_i32 s69, 0x6000
	s_mov_b32 s70, 0x18000
	s_mov_b32 s71, 0x3f317217
	s_and_b64 vcc, exec, s[28:29]
	s_cbranch_vccz .LBB0_1652
